# K-loop load segments: m0-hazard s_nop pads removed by issuing the address add between the m0 write and the LDS-DMA load
# baseline (speedup 1.0000x reference)
; #define PG8_STAGE(bufoff, gbase, voff) do { _Pragma("unroll") for (int _i = 0; _i < 2; ++_i) \
;         __builtin_amdgcn_global_load_lds((const unsigned*)((const char*)(gbase) + (voff)[_i]), (PG8_LAS unsigned*)(lds + (bufoff) + ldsw + _i * 8192), 16, 0, 0); } while (0)
; #define PG8_LDA(dst, b, h) do { _Pragma("unroll") for (int m = 0; m < 4; ++m) _Pragma("unroll") for (int k = 0; k < 2; ++k) dst[m][k] = *(const PG8_LAS bf16x8*)(lds + PG8_SA(b, h) + aoff + m * 2048 + k * 1024); } while (0)
; #define PG8_LDB(dst, b, h) do { _Pragma("unroll") for (int n = 0; n < 2; ++n) _Pragma("unroll") for (int k = 0; k < 2; ++k) dst[n][k] = *(const PG8_LAS bf16x8*)(lds + PG8_SB(b, h) + boff + n * 2048 + k * 1024); } while (0)
; #define PG8_WAIT_V(n) asm volatile("s_waitcnt vmcnt(" #n ")" ::: "memory")
; #define PG8_WAIT_L(n) asm volatile("s_waitcnt lgkmcnt(" #n ")" ::: "memory")
; #define PG8_BAR __builtin_amdgcn_s_barrier()
; template <class Epi, class Sched, bool ALIGN_EPI = false, bool SP2 = false>
; __device__ __forceinline__ void gemm_phase(PG8_LAS unsigned char* lds, const Gemm g, const Sched& S, const Epi& E) {
;     ...
;         const bool has_next = S.next(ui + 1, nxt);
;         const char* nA = has_next ? (const char*)g.A + (size_t)nxt.pm * tstep + (size_t)nxt.kt0 * kstep : cA; const char* nB = has_next ? (const char*)g.Bt + (size_t)nxt.pn * tstep + (size_t)nxt.kt0 * kstep : cB;
;         const int nt = cur.nt;
;         for (int t = 0; t < nt; t += 2) {
;             const bool last = (t == nt - 2);
;             const char* a1 = cA + (size_t)(t + 1) * kstep;
;             const char* a2 = last ? nA : cA + (size_t)(t + 2) * kstep; const char* b2 = last ? nB : cB + (size_t)(t + 2) * kstep;
;             const char* a3 = a2 + kstep; const char* b3 = b2 + kstep;
;             if (last && has_next) S.a_ready(nxt);
;             if constexpr (SP2) {
;             PG8_LDB(B0, 0, 0); PG8_LDB(B1, 0, 1); PG8_SCHED; PG8_LDA(At, 0, 0); PG8_STAGE(PG8_SA(1, 1), a1 + hstep, voffA);
;             PG8_WAIT_V(8); PG8_WAIT_L(0); PG8_BAR; PG8_MMA(0, 0, At, B0); PG8_MMA(0, 1, At, B1); PG8_BAR; PG8_SCHED;
;             PG8_LDA(At, 0, 1); PG8_STAGE(PG8_SB(0, 0), b2, voffB); PG8_STAGE(PG8_SB(0, 1), b2 + hstep, voffB); PG8_STAGE(PG8_SA(0, 0), a2, voffA);
;             PG8_WAIT_V(8); PG8_WAIT_L(0); PG8_BAR; PG8_MMA(1, 0, At, B0); PG8_MMA(1, 1, At, B1); PG8_BAR; PG8_SCHED;
.LBB0_235:
	s_ashr_i32 s41, s40, 31
	s_lshl_b64 s[42:43], s[40:41], 19
	s_add_u32 s42, s22, s42
	s_addc_u32 s43, s23, s43
	s_and_b64 s[44:45], s[36:37], exec
	s_cselect_b32 s66, s43, s87
	s_cselect_b32 s67, s42, s86
	s_ashr_i32 s39, s38, 31
	s_lshl_b64 s[44:45], s[38:39], 19
	s_add_u32 s44, s11, s44
	s_addc_u32 s45, s12, s45
	s_and_b64 s[68:69], s[36:37], exec
	s_cselect_b32 s39, s45, s89
	s_cselect_b32 s68, s44, s88
	s_add_u32 s86, s86, 0x40080
	s_addc_u32 s87, s87, 0
	s_add_u32 s69, s88, 0x100
	s_addc_u32 s71, s89, 0
	s_mov_b32 s75, -2
	s_waitcnt vmcnt(0)
	s_add_u32 s76, s86, 0xfffc0080
	s_addc_u32 s77, s87, -1
	s_add_i32 s80, 0, 0x10000
	s_cmp_eq_u32 s75, 12
	s_cselect_b32 s91, s66, s77
	s_cselect_b32 s90, s67, s76
	s_cselect_b32 s89, s39, s71
	s_cselect_b32 s88, s68, s69
	s_add_i32 s81, 0, 0x14000
	v_add_u32_e32 v154, s80, v176
	v_add_u32_e32 v186, s81, v176
	ds_read_b128 v[48:51], v154
	ds_read_b128 v[60:63], v154 offset:1024
	ds_read_b128 v[138:141], v154 offset:2048
	ds_read_b128 v[154:157], v154 offset:3072
	ds_read_b128 v[158:161], v186
	ds_read_b128 v[178:181], v186 offset:1024
	ds_read_b128 v[182:185], v186 offset:2048
	ds_read_b128 v[186:189], v186 offset:3072
	v_lshl_add_u64 v[194:195], s[86:87], 0, v[150:151]
	s_add_i32 m0, s15, 0xc000
	ds_read_b128 v[190:193], v177
	ds_read_b128 v[212:215], v177 offset:1024
	ds_read_b128 v[216:219], v177 offset:2048
	ds_read_b128 v[220:223], v177 offset:3072
	ds_read_b128 v[224:227], v177 offset:4096
	ds_read_b128 v[228:231], v177 offset:5120
	ds_read_b128 v[232:235], v177 offset:6144
	ds_read_b128 v[236:239], v177 offset:7168
	global_load_lds_dwordx4 v[194:195], off
	s_add_i32 m0, s15, 0xe000
	v_lshl_add_u64 v[194:195], s[86:87], 0, v[152:153]
	global_load_lds_dwordx4 v[194:195], off
	s_waitcnt vmcnt(8)
	s_waitcnt lgkmcnt(0)
	s_barrier
	s_setprio 1
	s_waitcnt lgkmcnt(0)
	v_mfma_f32_16x16x32_bf16 v[134:137], v[48:51], v[190:193], 0
	v_mfma_f32_16x16x32_bf16 v[126:129], v[138:141], v[190:193], 0
	v_mfma_f32_16x16x32_bf16 v[110:113], v[138:141], v[216:219], 0
	v_mfma_f32_16x16x32_bf16 v[118:121], v[48:51], v[216:219], 0
	v_mfma_f32_16x16x32_bf16 v[102:105], v[48:51], v[224:227], 0
	v_mfma_f32_16x16x32_bf16 v[94:97], v[138:141], v[224:227], 0
	v_mfma_f32_16x16x32_bf16 v[76:79], v[138:141], v[232:235], 0
	v_mfma_f32_16x16x32_bf16 v[86:89], v[48:51], v[232:235], 0
	v_mfma_f32_16x16x32_bf16 v[134:137], v[60:63], v[212:215], v[134:137]
	v_mfma_f32_16x16x32_bf16 v[126:129], v[154:157], v[212:215], v[126:129]
	v_mfma_f32_16x16x32_bf16 v[110:113], v[154:157], v[220:223], v[110:113]
	v_mfma_f32_16x16x32_bf16 v[118:121], v[60:63], v[220:223], v[118:121]
	v_mfma_f32_16x16x32_bf16 v[102:105], v[60:63], v[228:231], v[102:105]
	v_mfma_f32_16x16x32_bf16 v[94:97], v[154:157], v[228:231], v[94:97]
	v_mfma_f32_16x16x32_bf16 v[76:79], v[154:157], v[236:239], v[76:79]
	v_mfma_f32_16x16x32_bf16 v[86:89], v[60:63], v[236:239], v[86:89]
	v_mfma_f32_16x16x32_bf16 v[130:133], v[158:161], v[190:193], 0
	v_mfma_f32_16x16x32_bf16 v[122:125], v[182:185], v[190:193], 0
	v_mfma_f32_16x16x32_bf16 v[106:109], v[182:185], v[216:219], 0
	v_mfma_f32_16x16x32_bf16 v[114:117], v[158:161], v[216:219], 0
	v_mfma_f32_16x16x32_bf16 v[98:101], v[158:161], v[224:227], 0
	v_mfma_f32_16x16x32_bf16 v[90:93], v[182:185], v[224:227], 0
	v_mfma_f32_16x16x32_bf16 v[72:75], v[182:185], v[232:235], 0
	v_mfma_f32_16x16x32_bf16 v[82:85], v[158:161], v[232:235], 0
	v_mfma_f32_16x16x32_bf16 v[130:133], v[178:181], v[212:215], v[130:133]
	v_mfma_f32_16x16x32_bf16 v[122:125], v[186:189], v[212:215], v[122:125]
	v_mfma_f32_16x16x32_bf16 v[106:109], v[186:189], v[220:223], v[106:109]
	v_mfma_f32_16x16x32_bf16 v[114:117], v[178:181], v[220:223], v[114:117]
	v_mfma_f32_16x16x32_bf16 v[98:101], v[178:181], v[228:231], v[98:101]
	v_mfma_f32_16x16x32_bf16 v[90:93], v[186:189], v[228:231], v[90:93]
	v_mfma_f32_16x16x32_bf16 v[72:75], v[186:189], v[236:239], v[72:75]
	v_mfma_f32_16x16x32_bf16 v[82:85], v[178:181], v[236:239], v[82:85]
	s_setprio 0
	s_barrier
	s_add_i32 s76, s80, s13
	v_lshl_add_u64 v[194:195], s[88:89], 0, v[144:145]
	s_mov_b32 m0, s76
	ds_read_b128 v[190:193], v177 offset:16384
	ds_read_b128 v[212:215], v177 offset:17408
	ds_read_b128 v[216:219], v177 offset:18432
	ds_read_b128 v[220:223], v177 offset:19456
	ds_read_b128 v[224:227], v177 offset:20480
	ds_read_b128 v[228:231], v177 offset:21504
	ds_read_b128 v[232:235], v177 offset:22528
	ds_read_b128 v[236:239], v177 offset:23552
	global_load_lds_dwordx4 v[194:195], off
	s_add_i32 m0, s76, 0x2000
	s_add_u32 s76, s88, 0x40000
	v_lshl_add_u64 v[240:241], s[88:89], 0, v[148:149]
	s_addc_u32 s77, s89, 0
	s_add_i32 s80, s81, s13
	global_load_lds_dwordx4 v[240:241], off
	v_lshl_add_u64 v[242:243], s[76:77], 0, v[144:145]
	s_mov_b32 m0, s80
	v_lshl_add_u64 v[244:245], s[90:91], 0, v[146:147]
	global_load_lds_dwordx4 v[242:243], off
	s_add_i32 m0, s80, 0x2000
	v_lshl_add_u64 v[242:243], s[76:77], 0, v[148:149]
	global_load_lds_dwordx4 v[242:243], off
	s_mov_b32 m0, s15
	v_lshl_add_u64 v[242:243], s[90:91], 0, v[142:143]
	global_load_lds_dwordx4 v[242:243], off
	s_mov_b32 m0, s16
	s_nop 0
	global_load_lds_dwordx4 v[244:245], off
	s_waitcnt vmcnt(8)
	s_waitcnt lgkmcnt(0)
	s_barrier
; #define PG8_STAGE(bufoff, gbase, voff) do { _Pragma("unroll") for (int _i = 0; _i < 2; ++_i) \
;         __builtin_amdgcn_global_load_lds((const unsigned*)((const char*)(gbase) + (voff)[_i]), (PG8_LAS unsigned*)(lds + (bufoff) + ldsw + _i * 8192), 16, 0, 0); } while (0)
; #define PG8_LDA(dst, b, h) do { _Pragma("unroll") for (int m = 0; m < 4; ++m) _Pragma("unroll") for (int k = 0; k < 2; ++k) dst[m][k] = *(const PG8_LAS bf16x8*)(lds + PG8_SA(b, h) + aoff + m * 2048 + k * 1024); } while (0)
; #define PG8_LDB(dst, b, h) do { _Pragma("unroll") for (int n = 0; n < 2; ++n) _Pragma("unroll") for (int k = 0; k < 2; ++k) dst[n][k] = *(const PG8_LAS bf16x8*)(lds + PG8_SB(b, h) + boff + n * 2048 + k * 1024); } while (0)
; #define PG8_MMA(ai, bj, At, Bt) do { __builtin_amdgcn_s_setprio(1); _Pragma("unroll") for (int m = 0; m < 4; ++m) _Pragma("unroll") for (int n = 0; n < 2; ++n) _Pragma("unroll") for (int k = 0; k < 2; ++k) \
;         acc[ai][bj][m][n] = __builtin_amdgcn_mfma_f32_16x16x32_bf16(Bt[n][k], At[m][k], acc[ai][bj][m][n], 0, 0, 0); __builtin_amdgcn_s_setprio(0); } while (0)
; #define PG8_WAIT_V(n) asm volatile("s_waitcnt vmcnt(" #n ")" ::: "memory")
; #define PG8_WAIT_L(n) asm volatile("s_waitcnt lgkmcnt(" #n ")" ::: "memory")
; #define PG8_BAR __builtin_amdgcn_s_barrier()
; #define PG8_SCHED __builtin_amdgcn_sched_barrier(0)
; template <class Epi, class Sched, bool ALIGN_EPI = false, bool SP2 = false>
; __device__ __forceinline__ void gemm_phase(PG8_LAS unsigned char* lds, const Gemm g, const Sched& S, const Epi& E) {
;     ...
;             PG8_WAIT_V(8); PG8_WAIT_L(0); PG8_BAR; PG8_MMA(1, 0, At, B0); PG8_MMA(1, 1, At, B1); PG8_BAR; PG8_SCHED;
;             PG8_LDB(B0, 1, 0); PG8_LDB(B1, 1, 1); PG8_SCHED; PG8_LDA(At, 1, 0); PG8_STAGE(PG8_SA(0, 1), a2 + hstep, voffA);
;             PG8_WAIT_V(8); PG8_WAIT_L(0); PG8_BAR; PG8_MMA(0, 0, At, B0); PG8_MMA(0, 1, At, B1); PG8_BAR; PG8_SCHED;
	s_setprio 1
	s_waitcnt lgkmcnt(0)
	v_mfma_f32_16x16x32_bf16 v[68:71], v[48:51], v[190:193], 0
	v_mfma_f32_16x16x32_bf16 v[56:59], v[138:141], v[190:193], 0
	v_mfma_f32_16x16x32_bf16 v[36:39], v[138:141], v[216:219], 0
	v_mfma_f32_16x16x32_bf16 v[44:47], v[48:51], v[216:219], 0
	v_mfma_f32_16x16x32_bf16 v[28:31], v[48:51], v[224:227], 0
	v_mfma_f32_16x16x32_bf16 v[20:23], v[138:141], v[224:227], 0
	v_mfma_f32_16x16x32_bf16 v[4:7], v[138:141], v[232:235], 0
	v_mfma_f32_16x16x32_bf16 v[12:15], v[48:51], v[232:235], 0
	v_mfma_f32_16x16x32_bf16 v[68:71], v[60:63], v[212:215], v[68:71]
	v_mfma_f32_16x16x32_bf16 v[56:59], v[154:157], v[212:215], v[56:59]
	v_mfma_f32_16x16x32_bf16 v[36:39], v[154:157], v[220:223], v[36:39]
	v_mfma_f32_16x16x32_bf16 v[44:47], v[60:63], v[220:223], v[44:47]
	v_mfma_f32_16x16x32_bf16 v[28:31], v[60:63], v[228:231], v[28:31]
	v_mfma_f32_16x16x32_bf16 v[20:23], v[154:157], v[228:231], v[20:23]
	v_mfma_f32_16x16x32_bf16 v[4:7], v[154:157], v[236:239], v[4:7]
	v_mfma_f32_16x16x32_bf16 v[12:15], v[60:63], v[236:239], v[12:15]
	v_mfma_f32_16x16x32_bf16 v[52:55], v[182:185], v[190:193], 0
	v_mfma_f32_16x16x32_bf16 v[40:43], v[158:161], v[216:219], 0
	v_mfma_f32_16x16x32_bf16 v[32:35], v[182:185], v[216:219], 0
	v_mfma_f32_16x16x32_bf16 v[24:27], v[158:161], v[224:227], 0
	v_mfma_f32_16x16x32_bf16 v[16:19], v[182:185], v[224:227], 0
	v_mfma_f32_16x16x32_bf16 v[8:11], v[158:161], v[232:235], 0
	v_mfma_f32_16x16x32_bf16 v[0:3], v[182:185], v[232:235], 0
	v_mfma_f32_16x16x32_bf16 v[48:51], v[158:161], v[190:193], 0
	v_mfma_f32_16x16x32_bf16 v[52:55], v[186:189], v[212:215], v[52:55]
	v_mfma_f32_16x16x32_bf16 v[40:43], v[178:181], v[220:223], v[40:43]
	v_mfma_f32_16x16x32_bf16 v[32:35], v[186:189], v[220:223], v[32:35]
	v_mfma_f32_16x16x32_bf16 v[24:27], v[178:181], v[228:231], v[24:27]
	v_mfma_f32_16x16x32_bf16 v[16:19], v[186:189], v[228:231], v[16:19]
	v_mfma_f32_16x16x32_bf16 v[8:11], v[178:181], v[236:239], v[8:11]
	v_mfma_f32_16x16x32_bf16 v[0:3], v[186:189], v[236:239], v[0:3]
	v_mfma_f32_16x16x32_bf16 v[48:51], v[178:181], v[212:215], v[48:51]
	s_setprio 0
	s_barrier
	s_add_i32 s80, 0, 0x18000
	s_add_i32 s81, 0, 0x1c000
	v_add_u32_e32 v154, s80, v176
	v_add_u32_e32 v186, s81, v176
	ds_read_b128 v[60:63], v154
	ds_read_b128 v[64:67], v154 offset:1024
	ds_read_b128 v[138:141], v154 offset:2048
	ds_read_b128 v[154:157], v154 offset:3072
	ds_read_b128 v[158:161], v186
	ds_read_b128 v[178:181], v186 offset:1024
	ds_read_b128 v[182:185], v186 offset:2048
	ds_read_b128 v[186:189], v186 offset:3072
	s_add_u32 s76, s90, 0x40000
	s_addc_u32 s77, s91, 0
	s_mov_b32 m0, s17
	v_lshl_add_u64 v[246:247], s[76:77], 0, v[142:143]
	ds_read_b128 v[190:193], v177 offset:32768
	ds_read_b128 v[212:215], v177 offset:33792
	ds_read_b128 v[216:219], v177 offset:34816
	ds_read_b128 v[220:223], v177 offset:35840
	ds_read_b128 v[224:227], v177 offset:36864
	ds_read_b128 v[228:231], v177 offset:37888
	ds_read_b128 v[232:235], v177 offset:38912
	ds_read_b128 v[236:239], v177 offset:39936
	global_load_lds_dwordx4 v[246:247], off
	s_mov_b32 m0, s18
	v_lshl_add_u64 v[246:247], s[76:77], 0, v[146:147]
	global_load_lds_dwordx4 v[246:247], off
	s_waitcnt vmcnt(8)
	s_waitcnt lgkmcnt(0)
	s_barrier
	s_setprio 1
	s_waitcnt lgkmcnt(0)
	v_mfma_f32_16x16x32_bf16 v[134:137], v[60:63], v[190:193], v[134:137]
	v_mfma_f32_16x16x32_bf16 v[126:129], v[138:141], v[190:193], v[126:129]
	v_mfma_f32_16x16x32_bf16 v[110:113], v[138:141], v[216:219], v[110:113]
	v_mfma_f32_16x16x32_bf16 v[118:121], v[60:63], v[216:219], v[118:121]
	v_mfma_f32_16x16x32_bf16 v[102:105], v[60:63], v[224:227], v[102:105]
	v_mfma_f32_16x16x32_bf16 v[94:97], v[138:141], v[224:227], v[94:97]
	v_mfma_f32_16x16x32_bf16 v[76:79], v[138:141], v[232:235], v[76:79]
	v_mfma_f32_16x16x32_bf16 v[86:89], v[60:63], v[232:235], v[86:89]
	v_mfma_f32_16x16x32_bf16 v[134:137], v[64:67], v[212:215], v[134:137]
	v_mfma_f32_16x16x32_bf16 v[126:129], v[154:157], v[212:215], v[126:129]
	v_mfma_f32_16x16x32_bf16 v[110:113], v[154:157], v[220:223], v[110:113]
	v_mfma_f32_16x16x32_bf16 v[118:121], v[64:67], v[220:223], v[118:121]
	v_mfma_f32_16x16x32_bf16 v[102:105], v[64:67], v[228:231], v[102:105]
	v_mfma_f32_16x16x32_bf16 v[94:97], v[154:157], v[228:231], v[94:97]
	v_mfma_f32_16x16x32_bf16 v[76:79], v[154:157], v[236:239], v[76:79]
	v_mfma_f32_16x16x32_bf16 v[86:89], v[64:67], v[236:239], v[86:89]
	v_mfma_f32_16x16x32_bf16 v[130:133], v[158:161], v[190:193], v[130:133]
	v_mfma_f32_16x16x32_bf16 v[122:125], v[182:185], v[190:193], v[122:125]
	v_mfma_f32_16x16x32_bf16 v[106:109], v[182:185], v[216:219], v[106:109]
	v_mfma_f32_16x16x32_bf16 v[114:117], v[158:161], v[216:219], v[114:117]
	v_mfma_f32_16x16x32_bf16 v[98:101], v[158:161], v[224:227], v[98:101]
	v_mfma_f32_16x16x32_bf16 v[90:93], v[182:185], v[224:227], v[90:93]
	v_mfma_f32_16x16x32_bf16 v[72:75], v[182:185], v[232:235], v[72:75]
	v_mfma_f32_16x16x32_bf16 v[82:85], v[158:161], v[232:235], v[82:85]
	v_mfma_f32_16x16x32_bf16 v[130:133], v[178:181], v[212:215], v[130:133]
	v_mfma_f32_16x16x32_bf16 v[122:125], v[186:189], v[212:215], v[122:125]
	v_mfma_f32_16x16x32_bf16 v[106:109], v[186:189], v[220:223], v[106:109]
	v_mfma_f32_16x16x32_bf16 v[114:117], v[178:181], v[220:223], v[114:117]
	v_mfma_f32_16x16x32_bf16 v[98:101], v[178:181], v[228:231], v[98:101]
	v_mfma_f32_16x16x32_bf16 v[90:93], v[186:189], v[228:231], v[90:93]
	v_mfma_f32_16x16x32_bf16 v[72:75], v[186:189], v[236:239], v[72:75]
	v_mfma_f32_16x16x32_bf16 v[82:85], v[178:181], v[236:239], v[82:85]
	s_setprio 0
	s_barrier
; #define PG8_STAGE(bufoff, gbase, voff) do { _Pragma("unroll") for (int _i = 0; _i < 2; ++_i) \
;         __builtin_amdgcn_global_load_lds((const unsigned*)((const char*)(gbase) + (voff)[_i]), (PG8_LAS unsigned*)(lds + (bufoff) + ldsw + _i * 8192), 16, 0, 0); } while (0)
; #define PG8_LDA(dst, b, h) do { _Pragma("unroll") for (int m = 0; m < 4; ++m) _Pragma("unroll") for (int k = 0; k < 2; ++k) dst[m][k] = *(const PG8_LAS bf16x8*)(lds + PG8_SA(b, h) + aoff + m * 2048 + k * 1024); } while (0)
; #define PG8_LDB(dst, b, h) do { _Pragma("unroll") for (int n = 0; n < 2; ++n) _Pragma("unroll") for (int k = 0; k < 2; ++k) dst[n][k] = *(const PG8_LAS bf16x8*)(lds + PG8_SB(b, h) + boff + n * 2048 + k * 1024); } while (0)
; #define PG8_MMA(ai, bj, At, Bt) do { __builtin_amdgcn_s_setprio(1); _Pragma("unroll") for (int m = 0; m < 4; ++m) _Pragma("unroll") for (int n = 0; n < 2; ++n) _Pragma("unroll") for (int k = 0; k < 2; ++k) \
;         acc[ai][bj][m][n] = __builtin_amdgcn_mfma_f32_16x16x32_bf16(Bt[n][k], At[m][k], acc[ai][bj][m][n], 0, 0, 0); __builtin_amdgcn_s_setprio(0); } while (0)
; #define PG8_WAIT_V(n) asm volatile("s_waitcnt vmcnt(" #n ")" ::: "memory")
; template <class Epi, class Sched, bool ALIGN_EPI = false, bool SP2 = false>
; __device__ __forceinline__ void gemm_phase(PG8_LAS unsigned char* lds, const Gemm g, const Sched& S, const Epi& E) {
;     ...
;             PG8_LDB(B0, 0, 0); PG8_LDB(B1, 0, 1); PG8_SCHED; PG8_LDA(At, 0, 0); PG8_STAGE(PG8_SA(1, 1), a1 + hstep, voffA);
;             PG8_WAIT_V(8); PG8_WAIT_L(0); PG8_BAR; PG8_MMA(0, 0, At, B0); PG8_MMA(0, 1, At, B1); PG8_BAR; PG8_SCHED;
;             PG8_LDA(At, 0, 1); PG8_STAGE(PG8_SB(0, 0), b2, voffB); PG8_STAGE(PG8_SB(0, 1), b2 + hstep, voffB); PG8_STAGE(PG8_SA(0, 0), a2, voffA);
;             PG8_WAIT_V(8); PG8_WAIT_L(0); PG8_BAR; PG8_MMA(1, 0, At, B0); PG8_MMA(1, 1, At, B1); PG8_BAR; PG8_SCHED;
;             PG8_LDB(B0, 1, 0); PG8_LDB(B1, 1, 1); PG8_SCHED; PG8_LDA(At, 1, 0); PG8_STAGE(PG8_SA(0, 1), a2 + hstep, voffA);
;             PG8_WAIT_V(8); PG8_WAIT_L(0); PG8_BAR; PG8_MMA(0, 0, At, B0); PG8_MMA(0, 1, At, B1); PG8_BAR; PG8_SCHED;
;             PG8_LDA(At, 1, 1); PG8_STAGE(PG8_SB(1, 0), b3, voffB); PG8_STAGE(PG8_SB(1, 1), b3 + hstep, voffB); PG8_STAGE(PG8_SA(1, 0), a3, voffA);
;             PG8_WAIT_V(8); PG8_WAIT_L(0); PG8_BAR; PG8_MMA(1, 0, At, B0); PG8_MMA(1, 1, At, B1); PG8_BAR; PG8_SCHED;
	s_add_i32 s76, s80, s13
	v_lshl_add_u64 v[194:195], v[194:195], 0, s[0:1]
	s_mov_b32 m0, s76
	ds_read_b128 v[190:193], v177 offset:49152
	ds_read_b128 v[212:215], v177 offset:50176
	ds_read_b128 v[216:219], v177 offset:51200
	ds_read_b128 v[220:223], v177 offset:52224
	ds_read_b128 v[224:227], v177 offset:53248
	ds_read_b128 v[228:231], v177 offset:54272
	ds_read_b128 v[232:235], v177 offset:55296
	ds_read_b128 v[236:239], v177 offset:56320
	global_load_lds_dwordx4 v[194:195], off
	s_add_i32 m0, s76, 0x2000
	s_add_u32 s76, s88, 0x40080
	v_lshl_add_u64 v[194:195], v[240:241], 0, s[0:1]
	s_addc_u32 s77, s89, 0
	s_add_i32 s80, s81, s13
	global_load_lds_dwordx4 v[194:195], off
	s_mov_b32 m0, s80
	v_lshl_add_u64 v[194:195], s[76:77], 0, v[144:145]
	global_load_lds_dwordx4 v[194:195], off
	s_add_i32 m0, s80, 0x2000
	v_lshl_add_u64 v[194:195], s[76:77], 0, v[148:149]
	global_load_lds_dwordx4 v[194:195], off
	s_mov_b32 m0, s21
	v_lshl_add_u64 v[194:195], v[242:243], 0, s[0:1]
	global_load_lds_dwordx4 v[194:195], off
	s_mov_b32 m0, s33
	v_lshl_add_u64 v[194:195], v[244:245], 0, s[0:1]
	global_load_lds_dwordx4 v[194:195], off
	s_waitcnt vmcnt(8)
	s_waitcnt lgkmcnt(0)
	s_barrier
	s_setprio 1
	s_waitcnt lgkmcnt(0)
	v_mfma_f32_16x16x32_bf16 v[68:71], v[60:63], v[190:193], v[68:71]
	v_mfma_f32_16x16x32_bf16 v[56:59], v[138:141], v[190:193], v[56:59]
	v_mfma_f32_16x16x32_bf16 v[36:39], v[138:141], v[216:219], v[36:39]
	v_mfma_f32_16x16x32_bf16 v[44:47], v[60:63], v[216:219], v[44:47]
	v_mfma_f32_16x16x32_bf16 v[28:31], v[60:63], v[224:227], v[28:31]
	v_mfma_f32_16x16x32_bf16 v[20:23], v[138:141], v[224:227], v[20:23]
	v_mfma_f32_16x16x32_bf16 v[4:7], v[138:141], v[232:235], v[4:7]
	v_mfma_f32_16x16x32_bf16 v[12:15], v[60:63], v[232:235], v[12:15]
	v_mfma_f32_16x16x32_bf16 v[68:71], v[64:67], v[212:215], v[68:71]
	v_mfma_f32_16x16x32_bf16 v[56:59], v[154:157], v[212:215], v[56:59]
	v_mfma_f32_16x16x32_bf16 v[36:39], v[154:157], v[220:223], v[36:39]
	v_mfma_f32_16x16x32_bf16 v[44:47], v[64:67], v[220:223], v[44:47]
	v_mfma_f32_16x16x32_bf16 v[28:31], v[64:67], v[228:231], v[28:31]
	v_mfma_f32_16x16x32_bf16 v[20:23], v[154:157], v[228:231], v[20:23]
	v_mfma_f32_16x16x32_bf16 v[4:7], v[154:157], v[236:239], v[4:7]
	v_mfma_f32_16x16x32_bf16 v[12:15], v[64:67], v[236:239], v[12:15]
	v_mfma_f32_16x16x32_bf16 v[48:51], v[158:161], v[190:193], v[48:51]
	v_mfma_f32_16x16x32_bf16 v[64:67], v[178:181], v[212:215], v[48:51]
	v_mfma_f32_16x16x32_bf16 v[48:51], v[182:185], v[190:193], v[52:55]
	v_mfma_f32_16x16x32_bf16 v[40:43], v[158:161], v[216:219], v[40:43]
	v_mfma_f32_16x16x32_bf16 v[32:35], v[182:185], v[216:219], v[32:35]
	v_mfma_f32_16x16x32_bf16 v[24:27], v[158:161], v[224:227], v[24:27]
	v_mfma_f32_16x16x32_bf16 v[16:19], v[182:185], v[224:227], v[16:19]
	v_mfma_f32_16x16x32_bf16 v[8:11], v[158:161], v[232:235], v[8:11]
	v_mfma_f32_16x16x32_bf16 v[0:3], v[182:185], v[232:235], v[0:3]
	v_mfma_f32_16x16x32_bf16 v[52:55], v[186:189], v[212:215], v[48:51]
	v_mfma_f32_16x16x32_bf16 v[40:43], v[178:181], v[220:223], v[40:43]
	v_mfma_f32_16x16x32_bf16 v[32:35], v[186:189], v[220:223], v[32:35]
	v_mfma_f32_16x16x32_bf16 v[24:27], v[178:181], v[228:231], v[24:27]
	v_mfma_f32_16x16x32_bf16 v[16:19], v[186:189], v[228:231], v[16:19]
	v_mfma_f32_16x16x32_bf16 v[0:3], v[186:189], v[236:239], v[0:3]
	v_mfma_f32_16x16x32_bf16 v[8:11], v[178:181], v[236:239], v[8:11]
	s_setprio 0
	s_barrier
	s_add_i32 s75, s75, 2
	s_add_u32 s86, s86, 0x100
	s_addc_u32 s87, s87, 0
	s_add_u32 s69, s69, 0x100
	s_addc_u32 s71, s71, 0
	s_cmp_gt_u32 s75, 13
	s_cbranch_scc1 .Lpeel_done_2
.LBB0_236:
	s_add_u32 s76, s86, 0xfffc0080
	s_addc_u32 s77, s87, -1
	s_add_i32 s80, 0, 0x10000
	s_cmp_eq_u32 s75, 12
	s_cselect_b32 s91, s66, s77
	s_cselect_b32 s90, s67, s76
	s_cselect_b32 s89, s39, s71
	s_cselect_b32 s88, s68, s69
	s_add_i32 s81, 0, 0x14000
	v_add_u32_e32 v154, s80, v176
	v_add_u32_e32 v186, s81, v176
	ds_read_b128 v[48:51], v154
	ds_read_b128 v[60:63], v154 offset:1024
	ds_read_b128 v[138:141], v154 offset:2048
	ds_read_b128 v[154:157], v154 offset:3072
	ds_read_b128 v[158:161], v186
	ds_read_b128 v[178:181], v186 offset:1024
	ds_read_b128 v[182:185], v186 offset:2048
	ds_read_b128 v[186:189], v186 offset:3072
	v_lshl_add_u64 v[194:195], s[86:87], 0, v[150:151]
	s_add_i32 m0, s15, 0xc000
	ds_read_b128 v[190:193], v177
	ds_read_b128 v[212:215], v177 offset:1024
	ds_read_b128 v[216:219], v177 offset:2048
	ds_read_b128 v[220:223], v177 offset:3072
	ds_read_b128 v[224:227], v177 offset:4096
	ds_read_b128 v[228:231], v177 offset:5120
	ds_read_b128 v[232:235], v177 offset:6144
	ds_read_b128 v[236:239], v177 offset:7168
	global_load_lds_dwordx4 v[194:195], off
	s_add_i32 m0, s15, 0xe000
	v_lshl_add_u64 v[194:195], s[86:87], 0, v[152:153]
	global_load_lds_dwordx4 v[194:195], off
	s_waitcnt vmcnt(8)
	s_waitcnt lgkmcnt(0)
	s_barrier
; #define PG8_STAGE(bufoff, gbase, voff) do { _Pragma("unroll") for (int _i = 0; _i < 2; ++_i) \
;         __builtin_amdgcn_global_load_lds((const unsigned*)((const char*)(gbase) + (voff)[_i]), (PG8_LAS unsigned*)(lds + (bufoff) + ldsw + _i * 8192), 16, 0, 0); } while (0)
; #define PG8_LDA(dst, b, h) do { _Pragma("unroll") for (int m = 0; m < 4; ++m) _Pragma("unroll") for (int k = 0; k < 2; ++k) dst[m][k] = *(const PG8_LAS bf16x8*)(lds + PG8_SA(b, h) + aoff + m * 2048 + k * 1024); } while (0)
; #define PG8_MMA(ai, bj, At, Bt) do { __builtin_amdgcn_s_setprio(1); _Pragma("unroll") for (int m = 0; m < 4; ++m) _Pragma("unroll") for (int n = 0; n < 2; ++n) _Pragma("unroll") for (int k = 0; k < 2; ++k) \
;         acc[ai][bj][m][n] = __builtin_amdgcn_mfma_f32_16x16x32_bf16(Bt[n][k], At[m][k], acc[ai][bj][m][n], 0, 0, 0); __builtin_amdgcn_s_setprio(0); } while (0)
; #define PG8_WAIT_V(n) asm volatile("s_waitcnt vmcnt(" #n ")" ::: "memory")
; #define PG8_WAIT_L(n) asm volatile("s_waitcnt lgkmcnt(" #n ")" ::: "memory")
; #define PG8_BAR __builtin_amdgcn_s_barrier()
; #define PG8_SCHED __builtin_amdgcn_sched_barrier(0)
; template <class Epi, class Sched, bool ALIGN_EPI = false, bool SP2 = false>
; __device__ __forceinline__ void gemm_phase(PG8_LAS unsigned char* lds, const Gemm g, const Sched& S, const Epi& E) {
;     ...
;             PG8_WAIT_V(8); PG8_WAIT_L(0); PG8_BAR; PG8_MMA(0, 0, At, B0); PG8_MMA(0, 1, At, B1); PG8_BAR; PG8_SCHED;
;             PG8_LDA(At, 0, 1); PG8_STAGE(PG8_SB(0, 0), b2, voffB); PG8_STAGE(PG8_SB(0, 1), b2 + hstep, voffB); PG8_STAGE(PG8_SA(0, 0), a2, voffA);
;             PG8_WAIT_V(8); PG8_WAIT_L(0); PG8_BAR; PG8_MMA(1, 0, At, B0); PG8_MMA(1, 1, At, B1); PG8_BAR; PG8_SCHED;
	s_setprio 1
	s_waitcnt lgkmcnt(0)
	v_mfma_f32_16x16x32_bf16 v[134:137], v[48:51], v[190:193], v[134:137]
	v_mfma_f32_16x16x32_bf16 v[126:129], v[138:141], v[190:193], v[126:129]
	v_mfma_f32_16x16x32_bf16 v[110:113], v[138:141], v[216:219], v[110:113]
	v_mfma_f32_16x16x32_bf16 v[118:121], v[48:51], v[216:219], v[118:121]
	v_mfma_f32_16x16x32_bf16 v[102:105], v[48:51], v[224:227], v[102:105]
	v_mfma_f32_16x16x32_bf16 v[94:97], v[138:141], v[224:227], v[94:97]
	v_mfma_f32_16x16x32_bf16 v[76:79], v[138:141], v[232:235], v[76:79]
	v_mfma_f32_16x16x32_bf16 v[86:89], v[48:51], v[232:235], v[86:89]
	v_mfma_f32_16x16x32_bf16 v[134:137], v[60:63], v[212:215], v[134:137]
	v_mfma_f32_16x16x32_bf16 v[126:129], v[154:157], v[212:215], v[126:129]
	v_mfma_f32_16x16x32_bf16 v[110:113], v[154:157], v[220:223], v[110:113]
	v_mfma_f32_16x16x32_bf16 v[118:121], v[60:63], v[220:223], v[118:121]
	v_mfma_f32_16x16x32_bf16 v[102:105], v[60:63], v[228:231], v[102:105]
	v_mfma_f32_16x16x32_bf16 v[94:97], v[154:157], v[228:231], v[94:97]
	v_mfma_f32_16x16x32_bf16 v[76:79], v[154:157], v[236:239], v[76:79]
	v_mfma_f32_16x16x32_bf16 v[86:89], v[60:63], v[236:239], v[86:89]
	v_mfma_f32_16x16x32_bf16 v[130:133], v[158:161], v[190:193], v[130:133]
	v_mfma_f32_16x16x32_bf16 v[122:125], v[182:185], v[190:193], v[122:125]
	v_mfma_f32_16x16x32_bf16 v[106:109], v[182:185], v[216:219], v[106:109]
	v_mfma_f32_16x16x32_bf16 v[114:117], v[158:161], v[216:219], v[114:117]
	v_mfma_f32_16x16x32_bf16 v[98:101], v[158:161], v[224:227], v[98:101]
	v_mfma_f32_16x16x32_bf16 v[90:93], v[182:185], v[224:227], v[90:93]
	v_mfma_f32_16x16x32_bf16 v[72:75], v[182:185], v[232:235], v[72:75]
	v_mfma_f32_16x16x32_bf16 v[82:85], v[158:161], v[232:235], v[82:85]
	v_mfma_f32_16x16x32_bf16 v[130:133], v[178:181], v[212:215], v[130:133]
	v_mfma_f32_16x16x32_bf16 v[122:125], v[186:189], v[212:215], v[122:125]
	v_mfma_f32_16x16x32_bf16 v[106:109], v[186:189], v[220:223], v[106:109]
	v_mfma_f32_16x16x32_bf16 v[114:117], v[178:181], v[220:223], v[114:117]
	v_mfma_f32_16x16x32_bf16 v[98:101], v[178:181], v[228:231], v[98:101]
	v_mfma_f32_16x16x32_bf16 v[90:93], v[186:189], v[228:231], v[90:93]
	v_mfma_f32_16x16x32_bf16 v[72:75], v[186:189], v[236:239], v[72:75]
	v_mfma_f32_16x16x32_bf16 v[82:85], v[178:181], v[236:239], v[82:85]
	s_setprio 0
	s_barrier
	s_add_i32 s76, s80, s13
	v_lshl_add_u64 v[194:195], s[88:89], 0, v[144:145]
	s_mov_b32 m0, s76
	ds_read_b128 v[190:193], v177 offset:16384
	ds_read_b128 v[212:215], v177 offset:17408
	ds_read_b128 v[216:219], v177 offset:18432
	ds_read_b128 v[220:223], v177 offset:19456
	ds_read_b128 v[224:227], v177 offset:20480
	ds_read_b128 v[228:231], v177 offset:21504
	ds_read_b128 v[232:235], v177 offset:22528
	ds_read_b128 v[236:239], v177 offset:23552
	global_load_lds_dwordx4 v[194:195], off
	s_add_i32 m0, s76, 0x2000
	s_add_u32 s76, s88, 0x40000
	v_lshl_add_u64 v[240:241], s[88:89], 0, v[148:149]
	s_addc_u32 s77, s89, 0
	s_add_i32 s80, s81, s13
	global_load_lds_dwordx4 v[240:241], off
	v_lshl_add_u64 v[242:243], s[76:77], 0, v[144:145]
	s_mov_b32 m0, s80
	v_lshl_add_u64 v[244:245], s[90:91], 0, v[146:147]
	global_load_lds_dwordx4 v[242:243], off
	s_add_i32 m0, s80, 0x2000
	v_lshl_add_u64 v[242:243], s[76:77], 0, v[148:149]
	global_load_lds_dwordx4 v[242:243], off
	s_mov_b32 m0, s15
	v_lshl_add_u64 v[242:243], s[90:91], 0, v[142:143]
	global_load_lds_dwordx4 v[242:243], off
	s_mov_b32 m0, s16
	s_nop 0
	global_load_lds_dwordx4 v[244:245], off
	s_waitcnt vmcnt(8)
	s_waitcnt lgkmcnt(0)
	s_barrier
	s_setprio 1
	s_waitcnt lgkmcnt(0)
	v_mfma_f32_16x16x32_bf16 v[68:71], v[48:51], v[190:193], v[68:71]
	v_mfma_f32_16x16x32_bf16 v[56:59], v[138:141], v[190:193], v[56:59]
	v_mfma_f32_16x16x32_bf16 v[36:39], v[138:141], v[216:219], v[36:39]
	v_mfma_f32_16x16x32_bf16 v[44:47], v[48:51], v[216:219], v[44:47]
	v_mfma_f32_16x16x32_bf16 v[28:31], v[48:51], v[224:227], v[28:31]
	v_mfma_f32_16x16x32_bf16 v[20:23], v[138:141], v[224:227], v[20:23]
	v_mfma_f32_16x16x32_bf16 v[4:7], v[138:141], v[232:235], v[4:7]
	v_mfma_f32_16x16x32_bf16 v[12:15], v[48:51], v[232:235], v[12:15]
	v_mfma_f32_16x16x32_bf16 v[68:71], v[60:63], v[212:215], v[68:71]
	v_mfma_f32_16x16x32_bf16 v[56:59], v[154:157], v[212:215], v[56:59]
	v_mfma_f32_16x16x32_bf16 v[36:39], v[154:157], v[220:223], v[36:39]
	v_mfma_f32_16x16x32_bf16 v[44:47], v[60:63], v[220:223], v[44:47]
	v_mfma_f32_16x16x32_bf16 v[28:31], v[60:63], v[228:231], v[28:31]
	v_mfma_f32_16x16x32_bf16 v[20:23], v[154:157], v[228:231], v[20:23]
	v_mfma_f32_16x16x32_bf16 v[4:7], v[154:157], v[236:239], v[4:7]
	v_mfma_f32_16x16x32_bf16 v[12:15], v[60:63], v[236:239], v[12:15]
	v_mfma_f32_16x16x32_bf16 v[52:55], v[182:185], v[190:193], v[52:55]
	v_mfma_f32_16x16x32_bf16 v[40:43], v[158:161], v[216:219], v[40:43]
	v_mfma_f32_16x16x32_bf16 v[32:35], v[182:185], v[216:219], v[32:35]
	v_mfma_f32_16x16x32_bf16 v[24:27], v[158:161], v[224:227], v[24:27]
	v_mfma_f32_16x16x32_bf16 v[16:19], v[182:185], v[224:227], v[16:19]
	v_mfma_f32_16x16x32_bf16 v[8:11], v[158:161], v[232:235], v[8:11]
	v_mfma_f32_16x16x32_bf16 v[0:3], v[182:185], v[232:235], v[0:3]
	v_mfma_f32_16x16x32_bf16 v[48:51], v[158:161], v[190:193], v[64:67]
	v_mfma_f32_16x16x32_bf16 v[52:55], v[186:189], v[212:215], v[52:55]
	v_mfma_f32_16x16x32_bf16 v[40:43], v[178:181], v[220:223], v[40:43]
	v_mfma_f32_16x16x32_bf16 v[32:35], v[186:189], v[220:223], v[32:35]
	v_mfma_f32_16x16x32_bf16 v[24:27], v[178:181], v[228:231], v[24:27]
	v_mfma_f32_16x16x32_bf16 v[16:19], v[186:189], v[228:231], v[16:19]
	v_mfma_f32_16x16x32_bf16 v[8:11], v[178:181], v[236:239], v[8:11]
	v_mfma_f32_16x16x32_bf16 v[0:3], v[186:189], v[236:239], v[0:3]
	v_mfma_f32_16x16x32_bf16 v[48:51], v[178:181], v[212:215], v[48:51]
	s_setprio 0
	s_barrier
; #define PG8_STAGE(bufoff, gbase, voff) do { _Pragma("unroll") for (int _i = 0; _i < 2; ++_i) \
;         __builtin_amdgcn_global_load_lds((const unsigned*)((const char*)(gbase) + (voff)[_i]), (PG8_LAS unsigned*)(lds + (bufoff) + ldsw + _i * 8192), 16, 0, 0); } while (0)
; #define PG8_LDA(dst, b, h) do { _Pragma("unroll") for (int m = 0; m < 4; ++m) _Pragma("unroll") for (int k = 0; k < 2; ++k) dst[m][k] = *(const PG8_LAS bf16x8*)(lds + PG8_SA(b, h) + aoff + m * 2048 + k * 1024); } while (0)
; #define PG8_LDB(dst, b, h) do { _Pragma("unroll") for (int n = 0; n < 2; ++n) _Pragma("unroll") for (int k = 0; k < 2; ++k) dst[n][k] = *(const PG8_LAS bf16x8*)(lds + PG8_SB(b, h) + boff + n * 2048 + k * 1024); } while (0)
; #define PG8_MMA(ai, bj, At, Bt) do { __builtin_amdgcn_s_setprio(1); _Pragma("unroll") for (int m = 0; m < 4; ++m) _Pragma("unroll") for (int n = 0; n < 2; ++n) _Pragma("unroll") for (int k = 0; k < 2; ++k) \
;         acc[ai][bj][m][n] = __builtin_amdgcn_mfma_f32_16x16x32_bf16(Bt[n][k], At[m][k], acc[ai][bj][m][n], 0, 0, 0); __builtin_amdgcn_s_setprio(0); } while (0)
; #define PG8_WAIT_V(n) asm volatile("s_waitcnt vmcnt(" #n ")" ::: "memory")
; #define PG8_WAIT_L(n) asm volatile("s_waitcnt lgkmcnt(" #n ")" ::: "memory")
; #define PG8_BAR __builtin_amdgcn_s_barrier()
; #define PG8_SCHED __builtin_amdgcn_sched_barrier(0)
; template <class Epi, class Sched, bool ALIGN_EPI = false, bool SP2 = false>
; __device__ __forceinline__ void gemm_phase(PG8_LAS unsigned char* lds, const Gemm g, const Sched& S, const Epi& E) {
;     ...
;             PG8_LDB(B0, 1, 0); PG8_LDB(B1, 1, 1); PG8_SCHED; PG8_LDA(At, 1, 0); PG8_STAGE(PG8_SA(0, 1), a2 + hstep, voffA);
;             PG8_WAIT_V(8); PG8_WAIT_L(0); PG8_BAR; PG8_MMA(0, 0, At, B0); PG8_MMA(0, 1, At, B1); PG8_BAR; PG8_SCHED;
;             PG8_LDA(At, 1, 1); PG8_STAGE(PG8_SB(1, 0), b3, voffB); PG8_STAGE(PG8_SB(1, 1), b3 + hstep, voffB); PG8_STAGE(PG8_SA(1, 0), a3, voffA);
;             PG8_WAIT_V(8); PG8_WAIT_L(0); PG8_BAR; PG8_MMA(1, 0, At, B0); PG8_MMA(1, 1, At, B1); PG8_BAR; PG8_SCHED;
	s_add_i32 s80, 0, 0x18000
	s_add_i32 s81, 0, 0x1c000
	v_add_u32_e32 v154, s80, v176
	v_add_u32_e32 v186, s81, v176
	ds_read_b128 v[60:63], v154
	ds_read_b128 v[64:67], v154 offset:1024
	ds_read_b128 v[138:141], v154 offset:2048
	ds_read_b128 v[154:157], v154 offset:3072
	ds_read_b128 v[158:161], v186
	ds_read_b128 v[178:181], v186 offset:1024
	ds_read_b128 v[182:185], v186 offset:2048
	ds_read_b128 v[186:189], v186 offset:3072
	s_add_u32 s76, s90, 0x40000
	s_addc_u32 s77, s91, 0
	s_mov_b32 m0, s17
	v_lshl_add_u64 v[246:247], s[76:77], 0, v[142:143]
	ds_read_b128 v[190:193], v177 offset:32768
	ds_read_b128 v[212:215], v177 offset:33792
	ds_read_b128 v[216:219], v177 offset:34816
	ds_read_b128 v[220:223], v177 offset:35840
	ds_read_b128 v[224:227], v177 offset:36864
	ds_read_b128 v[228:231], v177 offset:37888
	ds_read_b128 v[232:235], v177 offset:38912
	ds_read_b128 v[236:239], v177 offset:39936
	global_load_lds_dwordx4 v[246:247], off
	s_mov_b32 m0, s18
	v_lshl_add_u64 v[246:247], s[76:77], 0, v[146:147]
	global_load_lds_dwordx4 v[246:247], off
	s_waitcnt vmcnt(8)
	s_waitcnt lgkmcnt(0)
	s_barrier
	s_setprio 1
	s_waitcnt lgkmcnt(0)
	v_mfma_f32_16x16x32_bf16 v[134:137], v[60:63], v[190:193], v[134:137]
	v_mfma_f32_16x16x32_bf16 v[126:129], v[138:141], v[190:193], v[126:129]
	v_mfma_f32_16x16x32_bf16 v[110:113], v[138:141], v[216:219], v[110:113]
	v_mfma_f32_16x16x32_bf16 v[118:121], v[60:63], v[216:219], v[118:121]
	v_mfma_f32_16x16x32_bf16 v[102:105], v[60:63], v[224:227], v[102:105]
	v_mfma_f32_16x16x32_bf16 v[94:97], v[138:141], v[224:227], v[94:97]
	v_mfma_f32_16x16x32_bf16 v[76:79], v[138:141], v[232:235], v[76:79]
	v_mfma_f32_16x16x32_bf16 v[86:89], v[60:63], v[232:235], v[86:89]
	v_mfma_f32_16x16x32_bf16 v[134:137], v[64:67], v[212:215], v[134:137]
	v_mfma_f32_16x16x32_bf16 v[126:129], v[154:157], v[212:215], v[126:129]
	v_mfma_f32_16x16x32_bf16 v[110:113], v[154:157], v[220:223], v[110:113]
	v_mfma_f32_16x16x32_bf16 v[118:121], v[64:67], v[220:223], v[118:121]
	v_mfma_f32_16x16x32_bf16 v[102:105], v[64:67], v[228:231], v[102:105]
	v_mfma_f32_16x16x32_bf16 v[94:97], v[154:157], v[228:231], v[94:97]
	v_mfma_f32_16x16x32_bf16 v[76:79], v[154:157], v[236:239], v[76:79]
	v_mfma_f32_16x16x32_bf16 v[86:89], v[64:67], v[236:239], v[86:89]
	v_mfma_f32_16x16x32_bf16 v[130:133], v[158:161], v[190:193], v[130:133]
	v_mfma_f32_16x16x32_bf16 v[122:125], v[182:185], v[190:193], v[122:125]
	v_mfma_f32_16x16x32_bf16 v[106:109], v[182:185], v[216:219], v[106:109]
	v_mfma_f32_16x16x32_bf16 v[114:117], v[158:161], v[216:219], v[114:117]
	v_mfma_f32_16x16x32_bf16 v[98:101], v[158:161], v[224:227], v[98:101]
	v_mfma_f32_16x16x32_bf16 v[90:93], v[182:185], v[224:227], v[90:93]
	v_mfma_f32_16x16x32_bf16 v[72:75], v[182:185], v[232:235], v[72:75]
	v_mfma_f32_16x16x32_bf16 v[82:85], v[158:161], v[232:235], v[82:85]
	v_mfma_f32_16x16x32_bf16 v[130:133], v[178:181], v[212:215], v[130:133]
	v_mfma_f32_16x16x32_bf16 v[122:125], v[186:189], v[212:215], v[122:125]
	v_mfma_f32_16x16x32_bf16 v[106:109], v[186:189], v[220:223], v[106:109]
	v_mfma_f32_16x16x32_bf16 v[114:117], v[178:181], v[220:223], v[114:117]
	v_mfma_f32_16x16x32_bf16 v[98:101], v[178:181], v[228:231], v[98:101]
	v_mfma_f32_16x16x32_bf16 v[90:93], v[186:189], v[228:231], v[90:93]
	v_mfma_f32_16x16x32_bf16 v[72:75], v[186:189], v[236:239], v[72:75]
	v_mfma_f32_16x16x32_bf16 v[82:85], v[178:181], v[236:239], v[82:85]
	s_setprio 0
	s_barrier
	s_add_i32 s76, s80, s13
	v_lshl_add_u64 v[194:195], v[194:195], 0, s[0:1]
	s_mov_b32 m0, s76
	ds_read_b128 v[190:193], v177 offset:49152
	ds_read_b128 v[212:215], v177 offset:50176
	ds_read_b128 v[216:219], v177 offset:51200
	ds_read_b128 v[220:223], v177 offset:52224
	ds_read_b128 v[224:227], v177 offset:53248
	ds_read_b128 v[228:231], v177 offset:54272
	ds_read_b128 v[232:235], v177 offset:55296
	ds_read_b128 v[236:239], v177 offset:56320
	global_load_lds_dwordx4 v[194:195], off
	s_add_i32 m0, s76, 0x2000
	s_add_u32 s76, s88, 0x40080
	v_lshl_add_u64 v[194:195], v[240:241], 0, s[0:1]
	s_addc_u32 s77, s89, 0
	s_add_i32 s80, s81, s13
	global_load_lds_dwordx4 v[194:195], off
	s_mov_b32 m0, s80
	v_lshl_add_u64 v[194:195], s[76:77], 0, v[144:145]
	global_load_lds_dwordx4 v[194:195], off
	s_add_i32 m0, s80, 0x2000
	v_lshl_add_u64 v[194:195], s[76:77], 0, v[148:149]
	global_load_lds_dwordx4 v[194:195], off
	s_mov_b32 m0, s21
	v_lshl_add_u64 v[194:195], v[242:243], 0, s[0:1]
	global_load_lds_dwordx4 v[194:195], off
	s_mov_b32 m0, s33
	v_lshl_add_u64 v[194:195], v[244:245], 0, s[0:1]
	global_load_lds_dwordx4 v[194:195], off
	s_waitcnt vmcnt(8)
	s_waitcnt lgkmcnt(0)
	s_barrier
	s_setprio 1
	s_waitcnt lgkmcnt(0)
	v_mfma_f32_16x16x32_bf16 v[68:71], v[60:63], v[190:193], v[68:71]
	v_mfma_f32_16x16x32_bf16 v[56:59], v[138:141], v[190:193], v[56:59]
	v_mfma_f32_16x16x32_bf16 v[36:39], v[138:141], v[216:219], v[36:39]
	v_mfma_f32_16x16x32_bf16 v[44:47], v[60:63], v[216:219], v[44:47]
	v_mfma_f32_16x16x32_bf16 v[28:31], v[60:63], v[224:227], v[28:31]
	v_mfma_f32_16x16x32_bf16 v[20:23], v[138:141], v[224:227], v[20:23]
	v_mfma_f32_16x16x32_bf16 v[4:7], v[138:141], v[232:235], v[4:7]
	v_mfma_f32_16x16x32_bf16 v[12:15], v[60:63], v[232:235], v[12:15]
	v_mfma_f32_16x16x32_bf16 v[68:71], v[64:67], v[212:215], v[68:71]
	v_mfma_f32_16x16x32_bf16 v[56:59], v[154:157], v[212:215], v[56:59]
	v_mfma_f32_16x16x32_bf16 v[36:39], v[154:157], v[220:223], v[36:39]
	v_mfma_f32_16x16x32_bf16 v[44:47], v[64:67], v[220:223], v[44:47]
	v_mfma_f32_16x16x32_bf16 v[28:31], v[64:67], v[228:231], v[28:31]
	v_mfma_f32_16x16x32_bf16 v[20:23], v[154:157], v[228:231], v[20:23]
	v_mfma_f32_16x16x32_bf16 v[4:7], v[154:157], v[236:239], v[4:7]
	v_mfma_f32_16x16x32_bf16 v[12:15], v[64:67], v[236:239], v[12:15]
	v_mfma_f32_16x16x32_bf16 v[48:51], v[158:161], v[190:193], v[48:51]
	v_mfma_f32_16x16x32_bf16 v[64:67], v[178:181], v[212:215], v[48:51]
	v_mfma_f32_16x16x32_bf16 v[48:51], v[182:185], v[190:193], v[52:55]
	v_mfma_f32_16x16x32_bf16 v[40:43], v[158:161], v[216:219], v[40:43]
	v_mfma_f32_16x16x32_bf16 v[32:35], v[182:185], v[216:219], v[32:35]
	v_mfma_f32_16x16x32_bf16 v[24:27], v[158:161], v[224:227], v[24:27]
	v_mfma_f32_16x16x32_bf16 v[16:19], v[182:185], v[224:227], v[16:19]
	v_mfma_f32_16x16x32_bf16 v[8:11], v[158:161], v[232:235], v[8:11]
	v_mfma_f32_16x16x32_bf16 v[0:3], v[182:185], v[232:235], v[0:3]
	v_mfma_f32_16x16x32_bf16 v[52:55], v[186:189], v[212:215], v[48:51]
	v_mfma_f32_16x16x32_bf16 v[40:43], v[178:181], v[220:223], v[40:43]
	v_mfma_f32_16x16x32_bf16 v[32:35], v[186:189], v[220:223], v[32:35]
	v_mfma_f32_16x16x32_bf16 v[24:27], v[178:181], v[228:231], v[24:27]
	v_mfma_f32_16x16x32_bf16 v[16:19], v[186:189], v[228:231], v[16:19]
	v_mfma_f32_16x16x32_bf16 v[0:3], v[186:189], v[236:239], v[0:3]
	v_mfma_f32_16x16x32_bf16 v[8:11], v[178:181], v[236:239], v[8:11]
	s_setprio 0
	s_barrier
	s_add_i32 s75, s75, 2
	s_add_u32 s86, s86, 0x100
	s_addc_u32 s87, s87, 0
	s_add_u32 s69, s69, 0x100
	s_addc_u32 s71, s71, 0
	s_cmp_gt_u32 s75, 13
	s_cbranch_scc0 .LBB0_236

; #define PG8_STAGE(bufoff, gbase, voff) do { _Pragma("unroll") for (int _i = 0; _i < 2; ++_i) \
;         __builtin_amdgcn_global_load_lds((const unsigned*)((const char*)(gbase) + (voff)[_i]), (PG8_LAS unsigned*)(lds + (bufoff) + ldsw + _i * 8192), 16, 0, 0); } while (0)
; #define PG8_LDA(dst, b, h) do { _Pragma("unroll") for (int m = 0; m < 4; ++m) _Pragma("unroll") for (int k = 0; k < 2; ++k) dst[m][k] = *(const PG8_LAS bf16x8*)(lds + PG8_SA(b, h) + aoff + m * 2048 + k * 1024); } while (0)
; #define PG8_LDB(dst, b, h) do { _Pragma("unroll") for (int n = 0; n < 2; ++n) _Pragma("unroll") for (int k = 0; k < 2; ++k) dst[n][k] = *(const PG8_LAS bf16x8*)(lds + PG8_SB(b, h) + boff + n * 2048 + k * 1024); } while (0)
; #define PG8_WAIT_V(n) asm volatile("s_waitcnt vmcnt(" #n ")" ::: "memory")
; #define PG8_WAIT_L(n) asm volatile("s_waitcnt lgkmcnt(" #n ")" ::: "memory")
; #define PG8_BAR __builtin_amdgcn_s_barrier()
; template <class Epi, class Sched, bool ALIGN_EPI = false, bool SP2 = false>
; __device__ __forceinline__ void gemm_phase(PG8_LAS unsigned char* lds, const Gemm g, const Sched& S, const Epi& E) {
;     ...
;         const bool has_next = S.next(ui + 1, nxt);
;         const char* nA = has_next ? (const char*)g.A + (size_t)nxt.pm * tstep + (size_t)nxt.kt0 * kstep : cA; const char* nB = has_next ? (const char*)g.Bt + (size_t)nxt.pn * tstep + (size_t)nxt.kt0 * kstep : cB;
;         const int nt = cur.nt;
;         for (int t = 0; t < nt; t += 2) {
;             const bool last = (t == nt - 2);
;             const char* a1 = cA + (size_t)(t + 1) * kstep;
;             const char* a2 = last ? nA : cA + (size_t)(t + 2) * kstep; const char* b2 = last ? nB : cB + (size_t)(t + 2) * kstep;
;             const char* a3 = a2 + kstep; const char* b3 = b2 + kstep;
;             if (last && has_next) S.a_ready(nxt);
;             if constexpr (SP2) {
;             PG8_LDB(B0, 0, 0); PG8_LDB(B1, 0, 1); PG8_SCHED; PG8_LDA(At, 0, 0); PG8_STAGE(PG8_SA(1, 1), a1 + hstep, voffA);
;             PG8_WAIT_V(8); PG8_WAIT_L(0); PG8_BAR; PG8_MMA(0, 0, At, B0); PG8_MMA(0, 1, At, B1); PG8_BAR; PG8_SCHED;
;             PG8_LDA(At, 0, 1); PG8_STAGE(PG8_SB(0, 0), b2, voffB); PG8_STAGE(PG8_SB(0, 1), b2 + hstep, voffB); PG8_STAGE(PG8_SA(0, 0), a2, voffA);
;             PG8_WAIT_V(8); PG8_WAIT_L(0); PG8_BAR; PG8_MMA(1, 0, At, B0); PG8_MMA(1, 1, At, B1); PG8_BAR; PG8_SCHED;
.LBB0_315:
	s_ashr_i32 s31, s30, 31
	s_lshl_b64 s[8:9], s[30:31], 19
	s_add_u32 s74, s68, s8
	s_addc_u32 s75, s69, s9
	s_and_b64 s[8:9], s[36:37], exec
	s_cselect_b32 s3, s75, s41
	s_cselect_b32 s8, s74, s40
	s_ashr_i32 s87, s86, 31
	s_lshl_b64 s[10:11], s[86:87], 19
	v_readlane_b32 s9, v252, 31
	s_add_u32 s88, s9, s10
	v_readlane_b32 s9, v252, 32
	s_addc_u32 s89, s9, s11
	s_and_b64 s[10:11], s[36:37], exec
	s_cselect_b32 s9, s89, s43
	s_cselect_b32 s10, s88, s42
	s_add_u32 s40, s40, 0x40080
	s_addc_u32 s41, s41, 0
	s_add_u32 s11, s42, 0x100
	s_addc_u32 s12, s43, 0
	s_mov_b32 s13, -2
	s_waitcnt vmcnt(0)
	s_add_u32 s14, s40, 0xfffc0080
	s_addc_u32 s15, s41, -1
	s_add_i32 s16, 0, 0x10000
	s_cmp_eq_u32 s13, 12
	s_cselect_b32 s71, s3, s15
	s_cselect_b32 s70, s8, s14
	s_cselect_b32 s43, s9, s12
	s_cselect_b32 s42, s10, s11
	s_add_i32 s17, 0, 0x14000
	s_waitcnt lgkmcnt(0)
	v_add_u32_e32 v44, s16, v214
	v_add_u32_e32 v102, s17, v214
	ds_read_b128 v[32:35], v44
	ds_read_b128 v[36:39], v44 offset:1024
	ds_read_b128 v[40:43], v44 offset:2048
	ds_read_b128 v[44:47], v44 offset:3072
	ds_read_b128 v[90:93], v102
	ds_read_b128 v[94:97], v102 offset:1024
	ds_read_b128 v[98:101], v102 offset:2048
	ds_read_b128 v[102:105], v102 offset:3072
	v_lshl_add_u64 v[194:195], s[40:41], 0, v[178:179]
	s_add_i32 m0, s97, 0xc000
	ds_read_b128 v[182:185], v215
	ds_read_b128 v[186:189], v215 offset:1024
	ds_read_b128 v[190:193], v215 offset:2048
	ds_read_b128 v[216:219], v215 offset:3072
	ds_read_b128 v[220:223], v215 offset:4096
	ds_read_b128 v[224:227], v215 offset:5120
	ds_read_b128 v[228:231], v215 offset:6144
	ds_read_b128 v[232:235], v215 offset:7168
	global_load_lds_dwordx4 v[194:195], off
	s_add_i32 m0, s97, 0xe000
	v_lshl_add_u64 v[194:195], s[40:41], 0, v[180:181]
	global_load_lds_dwordx4 v[194:195], off
	s_waitcnt vmcnt(8)
	s_waitcnt lgkmcnt(0)
	s_barrier
	s_setprio 1
	s_waitcnt lgkmcnt(0)
	v_mfma_f32_16x16x32_bf16 v[158:161], v[32:35], v[182:185], 0
	v_mfma_f32_16x16x32_bf16 v[154:157], v[40:43], v[182:185], 0
	v_mfma_f32_16x16x32_bf16 v[138:141], v[40:43], v[190:193], 0
	v_mfma_f32_16x16x32_bf16 v[142:145], v[32:35], v[190:193], 0
	v_mfma_f32_16x16x32_bf16 v[126:129], v[32:35], v[220:223], 0
	v_mfma_f32_16x16x32_bf16 v[122:125], v[40:43], v[220:223], 0
	v_mfma_f32_16x16x32_bf16 v[106:109], v[40:43], v[228:231], 0
	v_mfma_f32_16x16x32_bf16 v[110:113], v[32:35], v[228:231], 0
	v_mfma_f32_16x16x32_bf16 v[158:161], v[36:39], v[186:189], v[158:161]
	v_mfma_f32_16x16x32_bf16 v[154:157], v[44:47], v[186:189], v[154:157]
	v_mfma_f32_16x16x32_bf16 v[138:141], v[44:47], v[216:219], v[138:141]
	v_mfma_f32_16x16x32_bf16 v[142:145], v[36:39], v[216:219], v[142:145]
	v_mfma_f32_16x16x32_bf16 v[126:129], v[36:39], v[224:227], v[126:129]
	v_mfma_f32_16x16x32_bf16 v[122:125], v[44:47], v[224:227], v[122:125]
	v_mfma_f32_16x16x32_bf16 v[106:109], v[44:47], v[232:235], v[106:109]
	v_mfma_f32_16x16x32_bf16 v[110:113], v[36:39], v[232:235], v[110:113]
	v_mfma_f32_16x16x32_bf16 v[150:153], v[90:93], v[182:185], 0
	v_mfma_f32_16x16x32_bf16 v[146:149], v[98:101], v[182:185], 0
	v_mfma_f32_16x16x32_bf16 v[130:133], v[98:101], v[190:193], 0
	v_mfma_f32_16x16x32_bf16 v[134:137], v[90:93], v[190:193], 0
	v_mfma_f32_16x16x32_bf16 v[118:121], v[90:93], v[220:223], 0
	v_mfma_f32_16x16x32_bf16 v[114:117], v[98:101], v[220:223], 0
	v_mfma_f32_16x16x32_bf16 v[82:85], v[98:101], v[228:231], 0
	v_mfma_f32_16x16x32_bf16 v[86:89], v[90:93], v[228:231], 0
	v_mfma_f32_16x16x32_bf16 v[150:153], v[94:97], v[186:189], v[150:153]
	v_mfma_f32_16x16x32_bf16 v[146:149], v[102:105], v[186:189], v[146:149]
	v_mfma_f32_16x16x32_bf16 v[130:133], v[102:105], v[216:219], v[130:133]
	v_mfma_f32_16x16x32_bf16 v[134:137], v[94:97], v[216:219], v[134:137]
	v_mfma_f32_16x16x32_bf16 v[118:121], v[94:97], v[224:227], v[118:121]
	v_mfma_f32_16x16x32_bf16 v[114:117], v[102:105], v[224:227], v[114:117]
	v_mfma_f32_16x16x32_bf16 v[82:85], v[102:105], v[232:235], v[82:85]
	v_mfma_f32_16x16x32_bf16 v[86:89], v[94:97], v[232:235], v[86:89]
	s_setprio 0
	s_barrier
	s_add_i32 s14, s16, s95
	v_lshl_add_u64 v[194:195], s[42:43], 0, v[174:175]
	s_mov_b32 m0, s14
	ds_read_b128 v[182:185], v215 offset:16384
	ds_read_b128 v[186:189], v215 offset:17408
	ds_read_b128 v[190:193], v215 offset:18432
	ds_read_b128 v[216:219], v215 offset:19456
	ds_read_b128 v[220:223], v215 offset:20480
	ds_read_b128 v[224:227], v215 offset:21504
	ds_read_b128 v[228:231], v215 offset:22528
	ds_read_b128 v[232:235], v215 offset:23552
	global_load_lds_dwordx4 v[194:195], off
	s_add_i32 m0, s14, 0x2000
	s_add_u32 s14, s42, 0x40000
	v_lshl_add_u64 v[236:237], s[42:43], 0, v[176:177]
	s_addc_u32 s15, s43, 0
	s_add_i32 s16, s17, s95
	global_load_lds_dwordx4 v[236:237], off
	v_lshl_add_u64 v[238:239], s[14:15], 0, v[174:175]
	s_mov_b32 m0, s16
	v_lshl_add_u64 v[240:241], s[70:71], 0, v[176:177]
	global_load_lds_dwordx4 v[238:239], off
	s_add_i32 m0, s16, 0x2000
	v_lshl_add_u64 v[238:239], s[14:15], 0, v[176:177]
	global_load_lds_dwordx4 v[238:239], off
	s_mov_b32 m0, s97
	v_lshl_add_u64 v[238:239], s[70:71], 0, v[174:175]
	global_load_lds_dwordx4 v[238:239], off
	s_mov_b32 m0, s98
	s_nop 0
	global_load_lds_dwordx4 v[240:241], off
	s_waitcnt vmcnt(8)
	s_waitcnt lgkmcnt(0)
	s_barrier
; #define PG8_STAGE(bufoff, gbase, voff) do { _Pragma("unroll") for (int _i = 0; _i < 2; ++_i) \
;         __builtin_amdgcn_global_load_lds((const unsigned*)((const char*)(gbase) + (voff)[_i]), (PG8_LAS unsigned*)(lds + (bufoff) + ldsw + _i * 8192), 16, 0, 0); } while (0)
; #define PG8_LDA(dst, b, h) do { _Pragma("unroll") for (int m = 0; m < 4; ++m) _Pragma("unroll") for (int k = 0; k < 2; ++k) dst[m][k] = *(const PG8_LAS bf16x8*)(lds + PG8_SA(b, h) + aoff + m * 2048 + k * 1024); } while (0)
; #define PG8_LDB(dst, b, h) do { _Pragma("unroll") for (int n = 0; n < 2; ++n) _Pragma("unroll") for (int k = 0; k < 2; ++k) dst[n][k] = *(const PG8_LAS bf16x8*)(lds + PG8_SB(b, h) + boff + n * 2048 + k * 1024); } while (0)
; #define PG8_MMA(ai, bj, At, Bt) do { __builtin_amdgcn_s_setprio(1); _Pragma("unroll") for (int m = 0; m < 4; ++m) _Pragma("unroll") for (int n = 0; n < 2; ++n) _Pragma("unroll") for (int k = 0; k < 2; ++k) \
;         acc[ai][bj][m][n] = __builtin_amdgcn_mfma_f32_16x16x32_bf16(Bt[n][k], At[m][k], acc[ai][bj][m][n], 0, 0, 0); __builtin_amdgcn_s_setprio(0); } while (0)
; #define PG8_WAIT_V(n) asm volatile("s_waitcnt vmcnt(" #n ")" ::: "memory")
; #define PG8_WAIT_L(n) asm volatile("s_waitcnt lgkmcnt(" #n ")" ::: "memory")
; #define PG8_BAR __builtin_amdgcn_s_barrier()
; #define PG8_SCHED __builtin_amdgcn_sched_barrier(0)
; template <class Epi, class Sched, bool ALIGN_EPI = false, bool SP2 = false>
; __device__ __forceinline__ void gemm_phase(PG8_LAS unsigned char* lds, const Gemm g, const Sched& S, const Epi& E) {
;     ...
;             PG8_WAIT_V(8); PG8_WAIT_L(0); PG8_BAR; PG8_MMA(1, 0, At, B0); PG8_MMA(1, 1, At, B1); PG8_BAR; PG8_SCHED;
;             PG8_LDB(B0, 1, 0); PG8_LDB(B1, 1, 1); PG8_SCHED; PG8_LDA(At, 1, 0); PG8_STAGE(PG8_SA(0, 1), a2 + hstep, voffA);
;             PG8_WAIT_V(8); PG8_WAIT_L(0); PG8_BAR; PG8_MMA(0, 0, At, B0); PG8_MMA(0, 1, At, B1); PG8_BAR; PG8_SCHED;
	s_setprio 1
	s_waitcnt lgkmcnt(0)
	v_mfma_f32_16x16x32_bf16 v[76:79], v[32:35], v[182:185], 0
	v_mfma_f32_16x16x32_bf16 v[72:75], v[40:43], v[182:185], 0
	v_mfma_f32_16x16x32_bf16 v[56:59], v[40:43], v[190:193], 0
	v_mfma_f32_16x16x32_bf16 v[60:63], v[32:35], v[190:193], 0
	v_mfma_f32_16x16x32_bf16 v[28:31], v[32:35], v[220:223], 0
	v_mfma_f32_16x16x32_bf16 v[24:27], v[40:43], v[220:223], 0
	v_mfma_f32_16x16x32_bf16 v[8:11], v[40:43], v[228:231], 0
	v_mfma_f32_16x16x32_bf16 v[12:15], v[32:35], v[228:231], 0
	v_mfma_f32_16x16x32_bf16 v[76:79], v[36:39], v[186:189], v[76:79]
	v_mfma_f32_16x16x32_bf16 v[72:75], v[44:47], v[186:189], v[72:75]
	v_mfma_f32_16x16x32_bf16 v[56:59], v[44:47], v[216:219], v[56:59]
	v_mfma_f32_16x16x32_bf16 v[60:63], v[36:39], v[216:219], v[60:63]
	v_mfma_f32_16x16x32_bf16 v[28:31], v[36:39], v[224:227], v[28:31]
	v_mfma_f32_16x16x32_bf16 v[24:27], v[44:47], v[224:227], v[24:27]
	v_mfma_f32_16x16x32_bf16 v[8:11], v[44:47], v[232:235], v[8:11]
	v_mfma_f32_16x16x32_bf16 v[12:15], v[36:39], v[232:235], v[12:15]
	v_mfma_f32_16x16x32_bf16 v[20:23], v[90:93], v[220:223], 0
	v_mfma_f32_16x16x32_bf16 v[16:19], v[98:101], v[220:223], 0
	v_mfma_f32_16x16x32_bf16 v[0:3], v[98:101], v[228:231], 0
	v_mfma_f32_16x16x32_bf16 v[4:7], v[90:93], v[228:231], 0
	v_mfma_f32_16x16x32_bf16 v[32:35], v[90:93], v[182:185], 0
	v_mfma_f32_16x16x32_bf16 v[36:39], v[98:101], v[182:185], 0
	v_mfma_f32_16x16x32_bf16 v[44:47], v[98:101], v[190:193], 0
	v_mfma_f32_16x16x32_bf16 v[40:43], v[90:93], v[190:193], 0
	v_mfma_f32_16x16x32_bf16 v[20:23], v[94:97], v[224:227], v[20:23]
	v_mfma_f32_16x16x32_bf16 v[16:19], v[102:105], v[224:227], v[16:19]
	v_mfma_f32_16x16x32_bf16 v[0:3], v[102:105], v[232:235], v[0:3]
	v_mfma_f32_16x16x32_bf16 v[4:7], v[94:97], v[232:235], v[4:7]
	v_mfma_f32_16x16x32_bf16 v[32:35], v[94:97], v[186:189], v[32:35]
	v_mfma_f32_16x16x32_bf16 v[36:39], v[102:105], v[186:189], v[36:39]
	v_mfma_f32_16x16x32_bf16 v[44:47], v[102:105], v[216:219], v[44:47]
	v_mfma_f32_16x16x32_bf16 v[40:43], v[94:97], v[216:219], v[40:43]
	s_setprio 0
	s_barrier
	s_add_i32 s16, 0, 0x18000
	s_add_i32 s17, 0, 0x1c000
	v_add_u32_e32 v68, s16, v214
	v_add_u32_e32 v102, s17, v214
	ds_read_b128 v[48:51], v68
	ds_read_b128 v[52:55], v68 offset:1024
	ds_read_b128 v[64:67], v68 offset:2048
	ds_read_b128 v[68:71], v68 offset:3072
	ds_read_b128 v[90:93], v102
	ds_read_b128 v[94:97], v102 offset:1024
	ds_read_b128 v[98:101], v102 offset:2048
	ds_read_b128 v[102:105], v102 offset:3072
	s_add_u32 s14, s70, 0x40000
	s_addc_u32 s15, s71, 0
	s_mov_b32 m0, s99
	v_lshl_add_u64 v[242:243], s[14:15], 0, v[174:175]
	ds_read_b128 v[182:185], v215 offset:32768
	ds_read_b128 v[186:189], v215 offset:33792
	ds_read_b128 v[190:193], v215 offset:34816
	ds_read_b128 v[216:219], v215 offset:35840
	ds_read_b128 v[220:223], v215 offset:36864
	ds_read_b128 v[224:227], v215 offset:37888
	ds_read_b128 v[228:231], v215 offset:38912
	ds_read_b128 v[232:235], v215 offset:39936
	global_load_lds_dwordx4 v[242:243], off
	s_mov_b32 m0, s94
	v_lshl_add_u64 v[242:243], s[14:15], 0, v[176:177]
	global_load_lds_dwordx4 v[242:243], off
	s_waitcnt vmcnt(8)
	s_waitcnt lgkmcnt(0)
	s_barrier
	s_setprio 1
	s_waitcnt lgkmcnt(0)
	v_mfma_f32_16x16x32_bf16 v[158:161], v[48:51], v[182:185], v[158:161]
	v_mfma_f32_16x16x32_bf16 v[154:157], v[64:67], v[182:185], v[154:157]
	v_mfma_f32_16x16x32_bf16 v[138:141], v[64:67], v[190:193], v[138:141]
	v_mfma_f32_16x16x32_bf16 v[142:145], v[48:51], v[190:193], v[142:145]
	v_mfma_f32_16x16x32_bf16 v[126:129], v[48:51], v[220:223], v[126:129]
	v_mfma_f32_16x16x32_bf16 v[122:125], v[64:67], v[220:223], v[122:125]
	v_mfma_f32_16x16x32_bf16 v[106:109], v[64:67], v[228:231], v[106:109]
	v_mfma_f32_16x16x32_bf16 v[110:113], v[48:51], v[228:231], v[110:113]
	v_mfma_f32_16x16x32_bf16 v[158:161], v[52:55], v[186:189], v[158:161]
	v_mfma_f32_16x16x32_bf16 v[154:157], v[68:71], v[186:189], v[154:157]
	v_mfma_f32_16x16x32_bf16 v[138:141], v[68:71], v[216:219], v[138:141]
	v_mfma_f32_16x16x32_bf16 v[142:145], v[52:55], v[216:219], v[142:145]
	v_mfma_f32_16x16x32_bf16 v[126:129], v[52:55], v[224:227], v[126:129]
	v_mfma_f32_16x16x32_bf16 v[122:125], v[68:71], v[224:227], v[122:125]
	v_mfma_f32_16x16x32_bf16 v[106:109], v[68:71], v[232:235], v[106:109]
	v_mfma_f32_16x16x32_bf16 v[110:113], v[52:55], v[232:235], v[110:113]
	v_mfma_f32_16x16x32_bf16 v[150:153], v[90:93], v[182:185], v[150:153]
	v_mfma_f32_16x16x32_bf16 v[146:149], v[98:101], v[182:185], v[146:149]
	v_mfma_f32_16x16x32_bf16 v[130:133], v[98:101], v[190:193], v[130:133]
	v_mfma_f32_16x16x32_bf16 v[134:137], v[90:93], v[190:193], v[134:137]
	v_mfma_f32_16x16x32_bf16 v[118:121], v[90:93], v[220:223], v[118:121]
	v_mfma_f32_16x16x32_bf16 v[114:117], v[98:101], v[220:223], v[114:117]
	v_mfma_f32_16x16x32_bf16 v[82:85], v[98:101], v[228:231], v[82:85]
	v_mfma_f32_16x16x32_bf16 v[86:89], v[90:93], v[228:231], v[86:89]
	v_mfma_f32_16x16x32_bf16 v[150:153], v[94:97], v[186:189], v[150:153]
	v_mfma_f32_16x16x32_bf16 v[146:149], v[102:105], v[186:189], v[146:149]
	v_mfma_f32_16x16x32_bf16 v[130:133], v[102:105], v[216:219], v[130:133]
	v_mfma_f32_16x16x32_bf16 v[134:137], v[94:97], v[216:219], v[134:137]
	v_mfma_f32_16x16x32_bf16 v[118:121], v[94:97], v[224:227], v[118:121]
	v_mfma_f32_16x16x32_bf16 v[114:117], v[102:105], v[224:227], v[114:117]
	v_mfma_f32_16x16x32_bf16 v[82:85], v[102:105], v[232:235], v[82:85]
	v_mfma_f32_16x16x32_bf16 v[86:89], v[94:97], v[232:235], v[86:89]
	s_setprio 0
	s_barrier
; #define PG8_STAGE(bufoff, gbase, voff) do { _Pragma("unroll") for (int _i = 0; _i < 2; ++_i) \
;         __builtin_amdgcn_global_load_lds((const unsigned*)((const char*)(gbase) + (voff)[_i]), (PG8_LAS unsigned*)(lds + (bufoff) + ldsw + _i * 8192), 16, 0, 0); } while (0)
; #define PG8_LDA(dst, b, h) do { _Pragma("unroll") for (int m = 0; m < 4; ++m) _Pragma("unroll") for (int k = 0; k < 2; ++k) dst[m][k] = *(const PG8_LAS bf16x8*)(lds + PG8_SA(b, h) + aoff + m * 2048 + k * 1024); } while (0)
; #define PG8_LDB(dst, b, h) do { _Pragma("unroll") for (int n = 0; n < 2; ++n) _Pragma("unroll") for (int k = 0; k < 2; ++k) dst[n][k] = *(const PG8_LAS bf16x8*)(lds + PG8_SB(b, h) + boff + n * 2048 + k * 1024); } while (0)
; #define PG8_MMA(ai, bj, At, Bt) do { __builtin_amdgcn_s_setprio(1); _Pragma("unroll") for (int m = 0; m < 4; ++m) _Pragma("unroll") for (int n = 0; n < 2; ++n) _Pragma("unroll") for (int k = 0; k < 2; ++k) \
;         acc[ai][bj][m][n] = __builtin_amdgcn_mfma_f32_16x16x32_bf16(Bt[n][k], At[m][k], acc[ai][bj][m][n], 0, 0, 0); __builtin_amdgcn_s_setprio(0); } while (0)
; #define PG8_WAIT_V(n) asm volatile("s_waitcnt vmcnt(" #n ")" ::: "memory")
; template <class Epi, class Sched, bool ALIGN_EPI = false, bool SP2 = false>
; __device__ __forceinline__ void gemm_phase(PG8_LAS unsigned char* lds, const Gemm g, const Sched& S, const Epi& E) {
;     ...
;             PG8_LDB(B0, 0, 0); PG8_LDB(B1, 0, 1); PG8_SCHED; PG8_LDA(At, 0, 0); PG8_STAGE(PG8_SA(1, 1), a1 + hstep, voffA);
;             PG8_WAIT_V(8); PG8_WAIT_L(0); PG8_BAR; PG8_MMA(0, 0, At, B0); PG8_MMA(0, 1, At, B1); PG8_BAR; PG8_SCHED;
;             PG8_LDA(At, 0, 1); PG8_STAGE(PG8_SB(0, 0), b2, voffB); PG8_STAGE(PG8_SB(0, 1), b2 + hstep, voffB); PG8_STAGE(PG8_SA(0, 0), a2, voffA);
;             PG8_WAIT_V(8); PG8_WAIT_L(0); PG8_BAR; PG8_MMA(1, 0, At, B0); PG8_MMA(1, 1, At, B1); PG8_BAR; PG8_SCHED;
;             PG8_LDB(B0, 1, 0); PG8_LDB(B1, 1, 1); PG8_SCHED; PG8_LDA(At, 1, 0); PG8_STAGE(PG8_SA(0, 1), a2 + hstep, voffA);
;             PG8_WAIT_V(8); PG8_WAIT_L(0); PG8_BAR; PG8_MMA(0, 0, At, B0); PG8_MMA(0, 1, At, B1); PG8_BAR; PG8_SCHED;
;             PG8_LDA(At, 1, 1); PG8_STAGE(PG8_SB(1, 0), b3, voffB); PG8_STAGE(PG8_SB(1, 1), b3 + hstep, voffB); PG8_STAGE(PG8_SA(1, 0), a3, voffA);
;             PG8_WAIT_V(8); PG8_WAIT_L(0); PG8_BAR; PG8_MMA(1, 0, At, B0); PG8_MMA(1, 1, At, B1); PG8_BAR; PG8_SCHED;
	s_add_i32 s14, s16, s95
	v_lshl_add_u64 v[194:195], v[194:195], 0, s[0:1]
	s_mov_b32 m0, s14
	ds_read_b128 v[182:185], v215 offset:49152
	ds_read_b128 v[186:189], v215 offset:50176
	ds_read_b128 v[190:193], v215 offset:51200
	ds_read_b128 v[216:219], v215 offset:52224
	ds_read_b128 v[220:223], v215 offset:53248
	ds_read_b128 v[224:227], v215 offset:54272
	ds_read_b128 v[228:231], v215 offset:55296
	ds_read_b128 v[232:235], v215 offset:56320
	global_load_lds_dwordx4 v[194:195], off
	s_add_i32 m0, s14, 0x2000
	s_add_u32 s14, s42, 0x40080
	v_lshl_add_u64 v[194:195], v[236:237], 0, s[0:1]
	s_addc_u32 s15, s43, 0
	s_add_i32 s16, s17, s95
	global_load_lds_dwordx4 v[194:195], off
	s_mov_b32 m0, s16
	v_lshl_add_u64 v[194:195], s[14:15], 0, v[174:175]
	global_load_lds_dwordx4 v[194:195], off
	s_add_i32 m0, s16, 0x2000
	v_lshl_add_u64 v[194:195], s[14:15], 0, v[176:177]
	global_load_lds_dwordx4 v[194:195], off
	s_mov_b32 m0, s44
	v_lshl_add_u64 v[194:195], v[238:239], 0, s[0:1]
	global_load_lds_dwordx4 v[194:195], off
	s_mov_b32 m0, s45
	v_lshl_add_u64 v[194:195], v[240:241], 0, s[0:1]
	global_load_lds_dwordx4 v[194:195], off
	s_waitcnt vmcnt(8)
	s_waitcnt lgkmcnt(0)
	s_barrier
	s_setprio 1
	s_waitcnt lgkmcnt(0)
	v_mfma_f32_16x16x32_bf16 v[76:79], v[48:51], v[182:185], v[76:79]
	v_mfma_f32_16x16x32_bf16 v[72:75], v[64:67], v[182:185], v[72:75]
	v_mfma_f32_16x16x32_bf16 v[56:59], v[64:67], v[190:193], v[56:59]
	v_mfma_f32_16x16x32_bf16 v[60:63], v[48:51], v[190:193], v[60:63]
	v_mfma_f32_16x16x32_bf16 v[28:31], v[48:51], v[220:223], v[28:31]
	v_mfma_f32_16x16x32_bf16 v[24:27], v[64:67], v[220:223], v[24:27]
	v_mfma_f32_16x16x32_bf16 v[8:11], v[64:67], v[228:231], v[8:11]
	v_mfma_f32_16x16x32_bf16 v[12:15], v[48:51], v[228:231], v[12:15]
	v_mfma_f32_16x16x32_bf16 v[76:79], v[52:55], v[186:189], v[76:79]
	v_mfma_f32_16x16x32_bf16 v[72:75], v[68:71], v[186:189], v[72:75]
	v_mfma_f32_16x16x32_bf16 v[56:59], v[68:71], v[216:219], v[56:59]
	v_mfma_f32_16x16x32_bf16 v[60:63], v[52:55], v[216:219], v[60:63]
	v_mfma_f32_16x16x32_bf16 v[28:31], v[52:55], v[224:227], v[28:31]
	v_mfma_f32_16x16x32_bf16 v[24:27], v[68:71], v[224:227], v[24:27]
	v_mfma_f32_16x16x32_bf16 v[8:11], v[68:71], v[232:235], v[8:11]
	v_mfma_f32_16x16x32_bf16 v[12:15], v[52:55], v[232:235], v[12:15]
	v_mfma_f32_16x16x32_bf16 v[32:35], v[90:93], v[182:185], v[32:35]
	v_mfma_f32_16x16x32_bf16 v[68:71], v[94:97], v[186:189], v[32:35]
	v_mfma_f32_16x16x32_bf16 v[32:35], v[98:101], v[182:185], v[36:39]
	v_mfma_f32_16x16x32_bf16 v[64:67], v[102:105], v[186:189], v[32:35]
	v_mfma_f32_16x16x32_bf16 v[32:35], v[90:93], v[190:193], v[40:43]
	v_mfma_f32_16x16x32_bf16 v[52:55], v[94:97], v[216:219], v[32:35]
	v_mfma_f32_16x16x32_bf16 v[32:35], v[98:101], v[190:193], v[44:47]
	v_mfma_f32_16x16x32_bf16 v[20:23], v[90:93], v[220:223], v[20:23]
	v_mfma_f32_16x16x32_bf16 v[16:19], v[98:101], v[220:223], v[16:19]
	v_mfma_f32_16x16x32_bf16 v[4:7], v[90:93], v[228:231], v[4:7]
	v_mfma_f32_16x16x32_bf16 v[0:3], v[98:101], v[228:231], v[0:3]
	v_mfma_f32_16x16x32_bf16 v[48:51], v[102:105], v[216:219], v[32:35]
	v_mfma_f32_16x16x32_bf16 v[20:23], v[94:97], v[224:227], v[20:23]
	v_mfma_f32_16x16x32_bf16 v[16:19], v[102:105], v[224:227], v[16:19]
	v_mfma_f32_16x16x32_bf16 v[0:3], v[102:105], v[232:235], v[0:3]
	v_mfma_f32_16x16x32_bf16 v[4:7], v[94:97], v[232:235], v[4:7]
	s_setprio 0
	s_barrier
	s_add_i32 s13, s13, 2
	s_add_u32 s40, s40, 0x100
	s_addc_u32 s41, s41, 0
	s_add_u32 s11, s11, 0x100
	s_addc_u32 s12, s12, 0
	s_cmp_gt_u32 s13, 13
	s_cbranch_scc1 .Lpeel_done_1
.LBB0_316:
	s_add_u32 s14, s40, 0xfffc0080
	s_addc_u32 s15, s41, -1
	s_add_i32 s16, 0, 0x10000
	s_cmp_eq_u32 s13, 12
	s_cselect_b32 s71, s3, s15
	s_cselect_b32 s70, s8, s14
	s_cselect_b32 s43, s9, s12
	s_cselect_b32 s42, s10, s11
	s_add_i32 s17, 0, 0x14000
	s_waitcnt lgkmcnt(0)
	v_add_u32_e32 v44, s16, v214
	v_add_u32_e32 v102, s17, v214
	ds_read_b128 v[32:35], v44
	ds_read_b128 v[36:39], v44 offset:1024
	ds_read_b128 v[40:43], v44 offset:2048
	ds_read_b128 v[44:47], v44 offset:3072
	ds_read_b128 v[90:93], v102
	ds_read_b128 v[94:97], v102 offset:1024
	ds_read_b128 v[98:101], v102 offset:2048
	ds_read_b128 v[102:105], v102 offset:3072
	v_lshl_add_u64 v[194:195], s[40:41], 0, v[178:179]
	s_add_i32 m0, s97, 0xc000
	ds_read_b128 v[182:185], v215
	ds_read_b128 v[186:189], v215 offset:1024
	ds_read_b128 v[190:193], v215 offset:2048
	ds_read_b128 v[216:219], v215 offset:3072
	ds_read_b128 v[220:223], v215 offset:4096
	ds_read_b128 v[224:227], v215 offset:5120
	ds_read_b128 v[228:231], v215 offset:6144
	ds_read_b128 v[232:235], v215 offset:7168
	global_load_lds_dwordx4 v[194:195], off
	s_add_i32 m0, s97, 0xe000
	v_lshl_add_u64 v[194:195], s[40:41], 0, v[180:181]
	global_load_lds_dwordx4 v[194:195], off
	s_waitcnt vmcnt(8)
	s_waitcnt lgkmcnt(0)
	s_barrier
; #define PG8_STAGE(bufoff, gbase, voff) do { _Pragma("unroll") for (int _i = 0; _i < 2; ++_i) \
;         __builtin_amdgcn_global_load_lds((const unsigned*)((const char*)(gbase) + (voff)[_i]), (PG8_LAS unsigned*)(lds + (bufoff) + ldsw + _i * 8192), 16, 0, 0); } while (0)
; #define PG8_LDA(dst, b, h) do { _Pragma("unroll") for (int m = 0; m < 4; ++m) _Pragma("unroll") for (int k = 0; k < 2; ++k) dst[m][k] = *(const PG8_LAS bf16x8*)(lds + PG8_SA(b, h) + aoff + m * 2048 + k * 1024); } while (0)
; #define PG8_MMA(ai, bj, At, Bt) do { __builtin_amdgcn_s_setprio(1); _Pragma("unroll") for (int m = 0; m < 4; ++m) _Pragma("unroll") for (int n = 0; n < 2; ++n) _Pragma("unroll") for (int k = 0; k < 2; ++k) \
;         acc[ai][bj][m][n] = __builtin_amdgcn_mfma_f32_16x16x32_bf16(Bt[n][k], At[m][k], acc[ai][bj][m][n], 0, 0, 0); __builtin_amdgcn_s_setprio(0); } while (0)
; #define PG8_WAIT_V(n) asm volatile("s_waitcnt vmcnt(" #n ")" ::: "memory")
; #define PG8_WAIT_L(n) asm volatile("s_waitcnt lgkmcnt(" #n ")" ::: "memory")
; #define PG8_BAR __builtin_amdgcn_s_barrier()
; #define PG8_SCHED __builtin_amdgcn_sched_barrier(0)
; template <class Epi, class Sched, bool ALIGN_EPI = false, bool SP2 = false>
; __device__ __forceinline__ void gemm_phase(PG8_LAS unsigned char* lds, const Gemm g, const Sched& S, const Epi& E) {
;     ...
;             PG8_WAIT_V(8); PG8_WAIT_L(0); PG8_BAR; PG8_MMA(0, 0, At, B0); PG8_MMA(0, 1, At, B1); PG8_BAR; PG8_SCHED;
;             PG8_LDA(At, 0, 1); PG8_STAGE(PG8_SB(0, 0), b2, voffB); PG8_STAGE(PG8_SB(0, 1), b2 + hstep, voffB); PG8_STAGE(PG8_SA(0, 0), a2, voffA);
;             PG8_WAIT_V(8); PG8_WAIT_L(0); PG8_BAR; PG8_MMA(1, 0, At, B0); PG8_MMA(1, 1, At, B1); PG8_BAR; PG8_SCHED;
	s_setprio 1
	s_waitcnt lgkmcnt(0)
	v_mfma_f32_16x16x32_bf16 v[158:161], v[32:35], v[182:185], v[158:161]
	v_mfma_f32_16x16x32_bf16 v[154:157], v[40:43], v[182:185], v[154:157]
	v_mfma_f32_16x16x32_bf16 v[138:141], v[40:43], v[190:193], v[138:141]
	v_mfma_f32_16x16x32_bf16 v[142:145], v[32:35], v[190:193], v[142:145]
	v_mfma_f32_16x16x32_bf16 v[126:129], v[32:35], v[220:223], v[126:129]
	v_mfma_f32_16x16x32_bf16 v[122:125], v[40:43], v[220:223], v[122:125]
	v_mfma_f32_16x16x32_bf16 v[106:109], v[40:43], v[228:231], v[106:109]
	v_mfma_f32_16x16x32_bf16 v[110:113], v[32:35], v[228:231], v[110:113]
	v_mfma_f32_16x16x32_bf16 v[158:161], v[36:39], v[186:189], v[158:161]
	v_mfma_f32_16x16x32_bf16 v[154:157], v[44:47], v[186:189], v[154:157]
	v_mfma_f32_16x16x32_bf16 v[138:141], v[44:47], v[216:219], v[138:141]
	v_mfma_f32_16x16x32_bf16 v[142:145], v[36:39], v[216:219], v[142:145]
	v_mfma_f32_16x16x32_bf16 v[126:129], v[36:39], v[224:227], v[126:129]
	v_mfma_f32_16x16x32_bf16 v[122:125], v[44:47], v[224:227], v[122:125]
	v_mfma_f32_16x16x32_bf16 v[106:109], v[44:47], v[232:235], v[106:109]
	v_mfma_f32_16x16x32_bf16 v[110:113], v[36:39], v[232:235], v[110:113]
	v_mfma_f32_16x16x32_bf16 v[150:153], v[90:93], v[182:185], v[150:153]
	v_mfma_f32_16x16x32_bf16 v[146:149], v[98:101], v[182:185], v[146:149]
	v_mfma_f32_16x16x32_bf16 v[130:133], v[98:101], v[190:193], v[130:133]
	v_mfma_f32_16x16x32_bf16 v[134:137], v[90:93], v[190:193], v[134:137]
	v_mfma_f32_16x16x32_bf16 v[118:121], v[90:93], v[220:223], v[118:121]
	v_mfma_f32_16x16x32_bf16 v[114:117], v[98:101], v[220:223], v[114:117]
	v_mfma_f32_16x16x32_bf16 v[82:85], v[98:101], v[228:231], v[82:85]
	v_mfma_f32_16x16x32_bf16 v[86:89], v[90:93], v[228:231], v[86:89]
	v_mfma_f32_16x16x32_bf16 v[150:153], v[94:97], v[186:189], v[150:153]
	v_mfma_f32_16x16x32_bf16 v[146:149], v[102:105], v[186:189], v[146:149]
	v_mfma_f32_16x16x32_bf16 v[130:133], v[102:105], v[216:219], v[130:133]
	v_mfma_f32_16x16x32_bf16 v[134:137], v[94:97], v[216:219], v[134:137]
	v_mfma_f32_16x16x32_bf16 v[118:121], v[94:97], v[224:227], v[118:121]
	v_mfma_f32_16x16x32_bf16 v[114:117], v[102:105], v[224:227], v[114:117]
	v_mfma_f32_16x16x32_bf16 v[82:85], v[102:105], v[232:235], v[82:85]
	v_mfma_f32_16x16x32_bf16 v[86:89], v[94:97], v[232:235], v[86:89]
	s_setprio 0
	s_barrier
	s_add_i32 s14, s16, s95
	v_lshl_add_u64 v[194:195], s[42:43], 0, v[174:175]
	s_mov_b32 m0, s14
	ds_read_b128 v[182:185], v215 offset:16384
	ds_read_b128 v[186:189], v215 offset:17408
	ds_read_b128 v[190:193], v215 offset:18432
	ds_read_b128 v[216:219], v215 offset:19456
	ds_read_b128 v[220:223], v215 offset:20480
	ds_read_b128 v[224:227], v215 offset:21504
	ds_read_b128 v[228:231], v215 offset:22528
	ds_read_b128 v[232:235], v215 offset:23552
	global_load_lds_dwordx4 v[194:195], off
	s_add_i32 m0, s14, 0x2000
	s_add_u32 s14, s42, 0x40000
	v_lshl_add_u64 v[236:237], s[42:43], 0, v[176:177]
	s_addc_u32 s15, s43, 0
	s_add_i32 s16, s17, s95
	global_load_lds_dwordx4 v[236:237], off
	v_lshl_add_u64 v[238:239], s[14:15], 0, v[174:175]
	s_mov_b32 m0, s16
	v_lshl_add_u64 v[240:241], s[70:71], 0, v[176:177]
	global_load_lds_dwordx4 v[238:239], off
	s_add_i32 m0, s16, 0x2000
	v_lshl_add_u64 v[238:239], s[14:15], 0, v[176:177]
	global_load_lds_dwordx4 v[238:239], off
	s_mov_b32 m0, s97
	v_lshl_add_u64 v[238:239], s[70:71], 0, v[174:175]
	global_load_lds_dwordx4 v[238:239], off
	s_mov_b32 m0, s98
	s_nop 0
	global_load_lds_dwordx4 v[240:241], off
	s_waitcnt vmcnt(8)
	s_waitcnt lgkmcnt(0)
	s_barrier
	s_setprio 1
	s_waitcnt lgkmcnt(0)
	v_mfma_f32_16x16x32_bf16 v[76:79], v[32:35], v[182:185], v[76:79]
	v_mfma_f32_16x16x32_bf16 v[72:75], v[40:43], v[182:185], v[72:75]
	v_mfma_f32_16x16x32_bf16 v[56:59], v[40:43], v[190:193], v[56:59]
	v_mfma_f32_16x16x32_bf16 v[60:63], v[32:35], v[190:193], v[60:63]
	v_mfma_f32_16x16x32_bf16 v[28:31], v[32:35], v[220:223], v[28:31]
	v_mfma_f32_16x16x32_bf16 v[24:27], v[40:43], v[220:223], v[24:27]
	v_mfma_f32_16x16x32_bf16 v[8:11], v[40:43], v[228:231], v[8:11]
	v_mfma_f32_16x16x32_bf16 v[12:15], v[32:35], v[228:231], v[12:15]
	v_mfma_f32_16x16x32_bf16 v[76:79], v[36:39], v[186:189], v[76:79]
	v_mfma_f32_16x16x32_bf16 v[72:75], v[44:47], v[186:189], v[72:75]
	v_mfma_f32_16x16x32_bf16 v[56:59], v[44:47], v[216:219], v[56:59]
	v_mfma_f32_16x16x32_bf16 v[60:63], v[36:39], v[216:219], v[60:63]
	v_mfma_f32_16x16x32_bf16 v[28:31], v[36:39], v[224:227], v[28:31]
	v_mfma_f32_16x16x32_bf16 v[24:27], v[44:47], v[224:227], v[24:27]
	v_mfma_f32_16x16x32_bf16 v[8:11], v[44:47], v[232:235], v[8:11]
	v_mfma_f32_16x16x32_bf16 v[12:15], v[36:39], v[232:235], v[12:15]
	v_mfma_f32_16x16x32_bf16 v[20:23], v[90:93], v[220:223], v[20:23]
	v_mfma_f32_16x16x32_bf16 v[16:19], v[98:101], v[220:223], v[16:19]
	v_mfma_f32_16x16x32_bf16 v[0:3], v[98:101], v[228:231], v[0:3]
	v_mfma_f32_16x16x32_bf16 v[4:7], v[90:93], v[228:231], v[4:7]
	v_mfma_f32_16x16x32_bf16 v[32:35], v[90:93], v[182:185], v[68:71]
	v_mfma_f32_16x16x32_bf16 v[36:39], v[98:101], v[182:185], v[64:67]
	v_mfma_f32_16x16x32_bf16 v[44:47], v[98:101], v[190:193], v[48:51]
	v_mfma_f32_16x16x32_bf16 v[40:43], v[90:93], v[190:193], v[52:55]
	v_mfma_f32_16x16x32_bf16 v[20:23], v[94:97], v[224:227], v[20:23]
	v_mfma_f32_16x16x32_bf16 v[16:19], v[102:105], v[224:227], v[16:19]
	v_mfma_f32_16x16x32_bf16 v[0:3], v[102:105], v[232:235], v[0:3]
	v_mfma_f32_16x16x32_bf16 v[4:7], v[94:97], v[232:235], v[4:7]
	v_mfma_f32_16x16x32_bf16 v[32:35], v[94:97], v[186:189], v[32:35]
	v_mfma_f32_16x16x32_bf16 v[36:39], v[102:105], v[186:189], v[36:39]
	v_mfma_f32_16x16x32_bf16 v[44:47], v[102:105], v[216:219], v[44:47]
	v_mfma_f32_16x16x32_bf16 v[40:43], v[94:97], v[216:219], v[40:43]
	s_setprio 0
	s_barrier
; #define PG8_STAGE(bufoff, gbase, voff) do { _Pragma("unroll") for (int _i = 0; _i < 2; ++_i) \
;         __builtin_amdgcn_global_load_lds((const unsigned*)((const char*)(gbase) + (voff)[_i]), (PG8_LAS unsigned*)(lds + (bufoff) + ldsw + _i * 8192), 16, 0, 0); } while (0)
; #define PG8_LDA(dst, b, h) do { _Pragma("unroll") for (int m = 0; m < 4; ++m) _Pragma("unroll") for (int k = 0; k < 2; ++k) dst[m][k] = *(const PG8_LAS bf16x8*)(lds + PG8_SA(b, h) + aoff + m * 2048 + k * 1024); } while (0)
; #define PG8_LDB(dst, b, h) do { _Pragma("unroll") for (int n = 0; n < 2; ++n) _Pragma("unroll") for (int k = 0; k < 2; ++k) dst[n][k] = *(const PG8_LAS bf16x8*)(lds + PG8_SB(b, h) + boff + n * 2048 + k * 1024); } while (0)
; #define PG8_MMA(ai, bj, At, Bt) do { __builtin_amdgcn_s_setprio(1); _Pragma("unroll") for (int m = 0; m < 4; ++m) _Pragma("unroll") for (int n = 0; n < 2; ++n) _Pragma("unroll") for (int k = 0; k < 2; ++k) \
;         acc[ai][bj][m][n] = __builtin_amdgcn_mfma_f32_16x16x32_bf16(Bt[n][k], At[m][k], acc[ai][bj][m][n], 0, 0, 0); __builtin_amdgcn_s_setprio(0); } while (0)
; #define PG8_WAIT_V(n) asm volatile("s_waitcnt vmcnt(" #n ")" ::: "memory")
; #define PG8_WAIT_L(n) asm volatile("s_waitcnt lgkmcnt(" #n ")" ::: "memory")
; #define PG8_BAR __builtin_amdgcn_s_barrier()
; #define PG8_SCHED __builtin_amdgcn_sched_barrier(0)
; template <class Epi, class Sched, bool ALIGN_EPI = false, bool SP2 = false>
; __device__ __forceinline__ void gemm_phase(PG8_LAS unsigned char* lds, const Gemm g, const Sched& S, const Epi& E) {
;     ...
;             PG8_LDB(B0, 1, 0); PG8_LDB(B1, 1, 1); PG8_SCHED; PG8_LDA(At, 1, 0); PG8_STAGE(PG8_SA(0, 1), a2 + hstep, voffA);
;             PG8_WAIT_V(8); PG8_WAIT_L(0); PG8_BAR; PG8_MMA(0, 0, At, B0); PG8_MMA(0, 1, At, B1); PG8_BAR; PG8_SCHED;
;             PG8_LDA(At, 1, 1); PG8_STAGE(PG8_SB(1, 0), b3, voffB); PG8_STAGE(PG8_SB(1, 1), b3 + hstep, voffB); PG8_STAGE(PG8_SA(1, 0), a3, voffA);
;             PG8_WAIT_V(8); PG8_WAIT_L(0); PG8_BAR; PG8_MMA(1, 0, At, B0); PG8_MMA(1, 1, At, B1); PG8_BAR; PG8_SCHED;
	s_add_i32 s16, 0, 0x18000
	s_add_i32 s17, 0, 0x1c000
	v_add_u32_e32 v68, s16, v214
	v_add_u32_e32 v102, s17, v214
	ds_read_b128 v[48:51], v68
	ds_read_b128 v[52:55], v68 offset:1024
	ds_read_b128 v[64:67], v68 offset:2048
	ds_read_b128 v[68:71], v68 offset:3072
	ds_read_b128 v[90:93], v102
	ds_read_b128 v[94:97], v102 offset:1024
	ds_read_b128 v[98:101], v102 offset:2048
	ds_read_b128 v[102:105], v102 offset:3072
	s_add_u32 s14, s70, 0x40000
	s_addc_u32 s15, s71, 0
	s_mov_b32 m0, s99
	v_lshl_add_u64 v[242:243], s[14:15], 0, v[174:175]
	ds_read_b128 v[182:185], v215 offset:32768
	ds_read_b128 v[186:189], v215 offset:33792
	ds_read_b128 v[190:193], v215 offset:34816
	ds_read_b128 v[216:219], v215 offset:35840
	ds_read_b128 v[220:223], v215 offset:36864
	ds_read_b128 v[224:227], v215 offset:37888
	ds_read_b128 v[228:231], v215 offset:38912
	ds_read_b128 v[232:235], v215 offset:39936
	global_load_lds_dwordx4 v[242:243], off
	s_mov_b32 m0, s94
	v_lshl_add_u64 v[242:243], s[14:15], 0, v[176:177]
	global_load_lds_dwordx4 v[242:243], off
	s_waitcnt vmcnt(8)
	s_waitcnt lgkmcnt(0)
	s_barrier
	s_setprio 1
	s_waitcnt lgkmcnt(0)
	v_mfma_f32_16x16x32_bf16 v[158:161], v[48:51], v[182:185], v[158:161]
	v_mfma_f32_16x16x32_bf16 v[154:157], v[64:67], v[182:185], v[154:157]
	v_mfma_f32_16x16x32_bf16 v[138:141], v[64:67], v[190:193], v[138:141]
	v_mfma_f32_16x16x32_bf16 v[142:145], v[48:51], v[190:193], v[142:145]
	v_mfma_f32_16x16x32_bf16 v[126:129], v[48:51], v[220:223], v[126:129]
	v_mfma_f32_16x16x32_bf16 v[122:125], v[64:67], v[220:223], v[122:125]
	v_mfma_f32_16x16x32_bf16 v[106:109], v[64:67], v[228:231], v[106:109]
	v_mfma_f32_16x16x32_bf16 v[110:113], v[48:51], v[228:231], v[110:113]
	v_mfma_f32_16x16x32_bf16 v[158:161], v[52:55], v[186:189], v[158:161]
	v_mfma_f32_16x16x32_bf16 v[154:157], v[68:71], v[186:189], v[154:157]
	v_mfma_f32_16x16x32_bf16 v[138:141], v[68:71], v[216:219], v[138:141]
	v_mfma_f32_16x16x32_bf16 v[142:145], v[52:55], v[216:219], v[142:145]
	v_mfma_f32_16x16x32_bf16 v[126:129], v[52:55], v[224:227], v[126:129]
	v_mfma_f32_16x16x32_bf16 v[122:125], v[68:71], v[224:227], v[122:125]
	v_mfma_f32_16x16x32_bf16 v[106:109], v[68:71], v[232:235], v[106:109]
	v_mfma_f32_16x16x32_bf16 v[110:113], v[52:55], v[232:235], v[110:113]
	v_mfma_f32_16x16x32_bf16 v[150:153], v[90:93], v[182:185], v[150:153]
	v_mfma_f32_16x16x32_bf16 v[146:149], v[98:101], v[182:185], v[146:149]
	v_mfma_f32_16x16x32_bf16 v[130:133], v[98:101], v[190:193], v[130:133]
	v_mfma_f32_16x16x32_bf16 v[134:137], v[90:93], v[190:193], v[134:137]
	v_mfma_f32_16x16x32_bf16 v[118:121], v[90:93], v[220:223], v[118:121]
	v_mfma_f32_16x16x32_bf16 v[114:117], v[98:101], v[220:223], v[114:117]
	v_mfma_f32_16x16x32_bf16 v[82:85], v[98:101], v[228:231], v[82:85]
	v_mfma_f32_16x16x32_bf16 v[86:89], v[90:93], v[228:231], v[86:89]
	v_mfma_f32_16x16x32_bf16 v[150:153], v[94:97], v[186:189], v[150:153]
	v_mfma_f32_16x16x32_bf16 v[146:149], v[102:105], v[186:189], v[146:149]
	v_mfma_f32_16x16x32_bf16 v[130:133], v[102:105], v[216:219], v[130:133]
	v_mfma_f32_16x16x32_bf16 v[134:137], v[94:97], v[216:219], v[134:137]
	v_mfma_f32_16x16x32_bf16 v[118:121], v[94:97], v[224:227], v[118:121]
	v_mfma_f32_16x16x32_bf16 v[114:117], v[102:105], v[224:227], v[114:117]
	v_mfma_f32_16x16x32_bf16 v[82:85], v[102:105], v[232:235], v[82:85]
	v_mfma_f32_16x16x32_bf16 v[86:89], v[94:97], v[232:235], v[86:89]
	s_setprio 0
	s_barrier
	s_add_i32 s14, s16, s95
	v_lshl_add_u64 v[194:195], v[194:195], 0, s[0:1]
	s_mov_b32 m0, s14
	ds_read_b128 v[182:185], v215 offset:49152
	ds_read_b128 v[186:189], v215 offset:50176
	ds_read_b128 v[190:193], v215 offset:51200
	ds_read_b128 v[216:219], v215 offset:52224
	ds_read_b128 v[220:223], v215 offset:53248
	ds_read_b128 v[224:227], v215 offset:54272
	ds_read_b128 v[228:231], v215 offset:55296
	ds_read_b128 v[232:235], v215 offset:56320
	global_load_lds_dwordx4 v[194:195], off
	s_add_i32 m0, s14, 0x2000
	s_add_u32 s14, s42, 0x40080
	v_lshl_add_u64 v[194:195], v[236:237], 0, s[0:1]
	s_addc_u32 s15, s43, 0
	s_add_i32 s16, s17, s95
	global_load_lds_dwordx4 v[194:195], off
	s_mov_b32 m0, s16
	v_lshl_add_u64 v[194:195], s[14:15], 0, v[174:175]
	global_load_lds_dwordx4 v[194:195], off
	s_add_i32 m0, s16, 0x2000
	v_lshl_add_u64 v[194:195], s[14:15], 0, v[176:177]
	global_load_lds_dwordx4 v[194:195], off
	s_mov_b32 m0, s44
	v_lshl_add_u64 v[194:195], v[238:239], 0, s[0:1]
	global_load_lds_dwordx4 v[194:195], off
	s_mov_b32 m0, s45
	v_lshl_add_u64 v[194:195], v[240:241], 0, s[0:1]
	global_load_lds_dwordx4 v[194:195], off
	s_waitcnt vmcnt(8)
	s_waitcnt lgkmcnt(0)
	s_barrier
	s_setprio 1
	s_waitcnt lgkmcnt(0)
	v_mfma_f32_16x16x32_bf16 v[76:79], v[48:51], v[182:185], v[76:79]
	v_mfma_f32_16x16x32_bf16 v[72:75], v[64:67], v[182:185], v[72:75]
	v_mfma_f32_16x16x32_bf16 v[56:59], v[64:67], v[190:193], v[56:59]
	v_mfma_f32_16x16x32_bf16 v[60:63], v[48:51], v[190:193], v[60:63]
	v_mfma_f32_16x16x32_bf16 v[28:31], v[48:51], v[220:223], v[28:31]
	v_mfma_f32_16x16x32_bf16 v[24:27], v[64:67], v[220:223], v[24:27]
	v_mfma_f32_16x16x32_bf16 v[8:11], v[64:67], v[228:231], v[8:11]
	v_mfma_f32_16x16x32_bf16 v[12:15], v[48:51], v[228:231], v[12:15]
	v_mfma_f32_16x16x32_bf16 v[76:79], v[52:55], v[186:189], v[76:79]
	v_mfma_f32_16x16x32_bf16 v[72:75], v[68:71], v[186:189], v[72:75]
	v_mfma_f32_16x16x32_bf16 v[56:59], v[68:71], v[216:219], v[56:59]
	v_mfma_f32_16x16x32_bf16 v[60:63], v[52:55], v[216:219], v[60:63]
	v_mfma_f32_16x16x32_bf16 v[28:31], v[52:55], v[224:227], v[28:31]
	v_mfma_f32_16x16x32_bf16 v[24:27], v[68:71], v[224:227], v[24:27]
	v_mfma_f32_16x16x32_bf16 v[8:11], v[68:71], v[232:235], v[8:11]
	v_mfma_f32_16x16x32_bf16 v[12:15], v[52:55], v[232:235], v[12:15]
	v_mfma_f32_16x16x32_bf16 v[32:35], v[90:93], v[182:185], v[32:35]
	v_mfma_f32_16x16x32_bf16 v[68:71], v[94:97], v[186:189], v[32:35]
	v_mfma_f32_16x16x32_bf16 v[32:35], v[98:101], v[182:185], v[36:39]
	v_mfma_f32_16x16x32_bf16 v[64:67], v[102:105], v[186:189], v[32:35]
	v_mfma_f32_16x16x32_bf16 v[32:35], v[90:93], v[190:193], v[40:43]
	v_mfma_f32_16x16x32_bf16 v[52:55], v[94:97], v[216:219], v[32:35]
	v_mfma_f32_16x16x32_bf16 v[32:35], v[98:101], v[190:193], v[44:47]
	v_mfma_f32_16x16x32_bf16 v[20:23], v[90:93], v[220:223], v[20:23]
	v_mfma_f32_16x16x32_bf16 v[16:19], v[98:101], v[220:223], v[16:19]
	v_mfma_f32_16x16x32_bf16 v[4:7], v[90:93], v[228:231], v[4:7]
	v_mfma_f32_16x16x32_bf16 v[0:3], v[98:101], v[228:231], v[0:3]
	v_mfma_f32_16x16x32_bf16 v[48:51], v[102:105], v[216:219], v[32:35]
	v_mfma_f32_16x16x32_bf16 v[20:23], v[94:97], v[224:227], v[20:23]
	v_mfma_f32_16x16x32_bf16 v[16:19], v[102:105], v[224:227], v[16:19]
	v_mfma_f32_16x16x32_bf16 v[0:3], v[102:105], v[232:235], v[0:3]
	v_mfma_f32_16x16x32_bf16 v[4:7], v[94:97], v[232:235], v[4:7]
	s_setprio 0
	s_barrier
	s_add_i32 s13, s13, 2
	s_add_u32 s40, s40, 0x100
	s_addc_u32 s41, s41, 0
	s_add_u32 s11, s11, 0x100
	s_addc_u32 s12, s12, 0
	s_cmp_gt_u32 s13, 13
	s_cbranch_scc0 .LBB0_316

; #define PG8_STAGE(bufoff, gbase, voff) do { _Pragma("unroll") for (int _i = 0; _i < 2; ++_i) \
;         __builtin_amdgcn_global_load_lds((const unsigned*)((const char*)(gbase) + (voff)[_i]), (PG8_LAS unsigned*)(lds + (bufoff) + ldsw + _i * 8192), 16, 0, 0); } while (0)
; #define PG8_LDA(dst, b, h) do { _Pragma("unroll") for (int m = 0; m < 4; ++m) _Pragma("unroll") for (int k = 0; k < 2; ++k) dst[m][k] = *(const PG8_LAS bf16x8*)(lds + PG8_SA(b, h) + aoff + m * 2048 + k * 1024); } while (0)
; #define PG8_LDB(dst, b, h) do { _Pragma("unroll") for (int n = 0; n < 2; ++n) _Pragma("unroll") for (int k = 0; k < 2; ++k) dst[n][k] = *(const PG8_LAS bf16x8*)(lds + PG8_SB(b, h) + boff + n * 2048 + k * 1024); } while (0)
; #define PG8_MMA(ai, bj, At, Bt) do { __builtin_amdgcn_s_setprio(1); _Pragma("unroll") for (int m = 0; m < 4; ++m) _Pragma("unroll") for (int n = 0; n < 2; ++n) _Pragma("unroll") for (int k = 0; k < 2; ++k) \
;         acc[ai][bj][m][n] = __builtin_amdgcn_mfma_f32_16x16x32_bf16(Bt[n][k], At[m][k], acc[ai][bj][m][n], 0, 0, 0); __builtin_amdgcn_s_setprio(0); } while (0)
; #define PG8_WAIT_V(n) asm volatile("s_waitcnt vmcnt(" #n ")" ::: "memory")
; template <class Epi, class Sched, bool ALIGN_EPI = false, bool SP2 = false>
; __device__ __forceinline__ void gemm_phase(PG8_LAS unsigned char* lds, const Gemm g, const Sched& S, const Epi& E) {
;     ...
;         const int nt = cur.nt;
;         for (int t = 0; t < nt; t += 2) {
;             const bool last = (t == nt - 2);
;             const char* a1 = cA + (size_t)(t + 1) * kstep;
;             const char* a2 = last ? nA : cA + (size_t)(t + 2) * kstep; const char* b2 = last ? nB : cB + (size_t)(t + 2) * kstep;
;             const char* a3 = a2 + kstep; const char* b3 = b2 + kstep;
;             if (last && has_next) S.a_ready(nxt);
;             if constexpr (SP2) {
;             PG8_LDB(B0, 0, 0); PG8_LDB(B1, 0, 1); PG8_SCHED; PG8_LDA(At, 0, 0); PG8_STAGE(PG8_SA(1, 1), a1 + hstep, voffA);
;             PG8_WAIT_V(8); PG8_WAIT_L(0); PG8_BAR; PG8_MMA(0, 0, At, B0); PG8_MMA(0, 1, At, B1); PG8_BAR; PG8_SCHED;
;             PG8_LDA(At, 0, 1); PG8_STAGE(PG8_SB(0, 0), b2, voffB); PG8_STAGE(PG8_SB(0, 1), b2 + hstep, voffB); PG8_STAGE(PG8_SA(0, 0), a2, voffA);
;             PG8_WAIT_V(8); PG8_WAIT_L(0); PG8_BAR; PG8_MMA(1, 0, At, B0); PG8_MMA(1, 1, At, B1); PG8_BAR; PG8_SCHED;
.LBB0_646:
	s_add_i32 s24, s44, -2
	s_add_u32 s38, s38, 0x80
	s_addc_u32 s39, s39, 0
	s_add_u32 s41, s42, 0x100
	s_addc_u32 s45, s43, 0
	s_mov_b32 s42, 0
	s_waitcnt lgkmcnt(0)
	s_waitcnt vmcnt(0)
	s_add_i32 s71, s42, 2
	s_add_u32 s81, s38, 0x80
	s_addc_u32 s43, s39, 0
	s_add_i32 s94, 0, 0x10000
	s_cmp_eq_u32 s24, s42
	s_cselect_b32 s43, s27, s43
	s_cselect_b32 s42, s26, s81
	s_cselect_b32 s93, s91, s45
	s_cselect_b32 s92, s90, s41
	s_add_i32 s81, 0, 0x14000
	v_add_u32_e32 v142, s94, v213
	v_add_u32_e32 v151, s81, v213
	ds_read_b128 v[130:133], v142
	ds_read_b128 v[134:137], v142 offset:1024
	ds_read_b128 v[138:141], v142 offset:2048
	ds_read_b128 v[142:145], v142 offset:3072
	ds_read_b128 v[158:161], v151
	ds_read_b128 v[174:177], v151 offset:1024
	ds_read_b128 v[178:181], v151 offset:2048
	ds_read_b128 v[182:185], v151 offset:3072
	v_lshl_add_u64 v[194:195], s[38:39], 0, v[154:155]
	s_add_i32 m0, s17, 0xc000
	ds_read_b128 v[186:189], v214
	ds_read_b128 v[190:193], v214 offset:1024
	ds_read_b128 v[216:219], v214 offset:2048
	ds_read_b128 v[220:223], v214 offset:3072
	ds_read_b128 v[224:227], v214 offset:4096
	ds_read_b128 v[228:231], v214 offset:5120
	ds_read_b128 v[232:235], v214 offset:6144
	ds_read_b128 v[236:239], v214 offset:7168
	global_load_lds_dwordx4 v[194:195], off
	s_add_i32 m0, s17, 0xe000
	v_lshl_add_u64 v[194:195], s[38:39], 0, v[156:157]
	global_load_lds_dwordx4 v[194:195], off
	s_waitcnt vmcnt(8)
	s_waitcnt lgkmcnt(0)
	s_barrier
	s_setprio 1
	s_waitcnt lgkmcnt(0)
	v_mfma_f32_16x16x32_bf16 v[126:129], v[130:133], v[186:189], 0
	v_mfma_f32_16x16x32_bf16 v[122:125], v[138:141], v[186:189], 0
	v_mfma_f32_16x16x32_bf16 v[106:109], v[138:141], v[216:219], 0
	v_mfma_f32_16x16x32_bf16 v[110:113], v[130:133], v[216:219], 0
	v_mfma_f32_16x16x32_bf16 v[94:97], v[130:133], v[224:227], 0
	v_mfma_f32_16x16x32_bf16 v[90:93], v[138:141], v[224:227], 0
	v_mfma_f32_16x16x32_bf16 v[72:75], v[138:141], v[232:235], 0
	v_mfma_f32_16x16x32_bf16 v[76:79], v[130:133], v[232:235], 0
	v_mfma_f32_16x16x32_bf16 v[126:129], v[134:137], v[190:193], v[126:129]
	v_mfma_f32_16x16x32_bf16 v[122:125], v[142:145], v[190:193], v[122:125]
	v_mfma_f32_16x16x32_bf16 v[106:109], v[142:145], v[220:223], v[106:109]
	v_mfma_f32_16x16x32_bf16 v[110:113], v[134:137], v[220:223], v[110:113]
	v_mfma_f32_16x16x32_bf16 v[94:97], v[134:137], v[228:231], v[94:97]
	v_mfma_f32_16x16x32_bf16 v[90:93], v[142:145], v[228:231], v[90:93]
	v_mfma_f32_16x16x32_bf16 v[72:75], v[142:145], v[236:239], v[72:75]
	v_mfma_f32_16x16x32_bf16 v[76:79], v[134:137], v[236:239], v[76:79]
	v_mfma_f32_16x16x32_bf16 v[118:121], v[158:161], v[186:189], 0
	v_mfma_f32_16x16x32_bf16 v[114:117], v[178:181], v[186:189], 0
	v_mfma_f32_16x16x32_bf16 v[98:101], v[178:181], v[216:219], 0
	v_mfma_f32_16x16x32_bf16 v[102:105], v[158:161], v[216:219], 0
	v_mfma_f32_16x16x32_bf16 v[86:89], v[158:161], v[224:227], 0
	v_mfma_f32_16x16x32_bf16 v[82:85], v[178:181], v[224:227], 0
	v_mfma_f32_16x16x32_bf16 v[64:67], v[178:181], v[232:235], 0
	v_mfma_f32_16x16x32_bf16 v[68:71], v[158:161], v[232:235], 0
	v_mfma_f32_16x16x32_bf16 v[118:121], v[174:177], v[190:193], v[118:121]
	v_mfma_f32_16x16x32_bf16 v[114:117], v[182:185], v[190:193], v[114:117]
	v_mfma_f32_16x16x32_bf16 v[98:101], v[182:185], v[220:223], v[98:101]
	v_mfma_f32_16x16x32_bf16 v[102:105], v[174:177], v[220:223], v[102:105]
	v_mfma_f32_16x16x32_bf16 v[86:89], v[174:177], v[228:231], v[86:89]
	v_mfma_f32_16x16x32_bf16 v[82:85], v[182:185], v[228:231], v[82:85]
	v_mfma_f32_16x16x32_bf16 v[64:67], v[182:185], v[236:239], v[64:67]
	v_mfma_f32_16x16x32_bf16 v[68:71], v[174:177], v[236:239], v[68:71]
	s_setprio 0
	s_barrier
	s_add_i32 s94, s94, s16
	v_lshl_add_u64 v[194:195], s[92:93], 0, v[146:147]
	s_mov_b32 m0, s94
	ds_read_b128 v[186:189], v214 offset:16384
	ds_read_b128 v[190:193], v214 offset:17408
	ds_read_b128 v[216:219], v214 offset:18432
	ds_read_b128 v[220:223], v214 offset:19456
	ds_read_b128 v[224:227], v214 offset:20480
	ds_read_b128 v[228:231], v214 offset:21504
	ds_read_b128 v[232:235], v214 offset:22528
	ds_read_b128 v[236:239], v214 offset:23552
	global_load_lds_dwordx4 v[194:195], off
	s_add_i32 m0, s94, 0x2000
	v_lshl_add_u64 v[240:241], s[92:93], 0, v[148:149]
	s_add_u32 s92, s92, s30
	s_addc_u32 s93, s93, 0
	s_add_i32 s81, s81, s16
	global_load_lds_dwordx4 v[240:241], off
	v_lshl_add_u64 v[242:243], s[92:93], 0, v[146:147]
	s_mov_b32 m0, s81
	v_lshl_add_u64 v[244:245], s[92:93], 0, v[148:149]
	global_load_lds_dwordx4 v[242:243], off
	s_add_i32 m0, s81, 0x2000
	v_lshl_add_u64 v[246:247], s[42:43], 0, v[146:147]
	global_load_lds_dwordx4 v[244:245], off
	s_mov_b32 m0, s17
	v_lshl_add_u64 v[248:249], s[42:43], 0, v[148:149]
	global_load_lds_dwordx4 v[246:247], off
	s_mov_b32 m0, s18
	s_nop 0
	global_load_lds_dwordx4 v[248:249], off
	s_waitcnt vmcnt(8)
	s_waitcnt lgkmcnt(0)
	s_barrier
; #define PG8_STAGE(bufoff, gbase, voff) do { _Pragma("unroll") for (int _i = 0; _i < 2; ++_i) \
;         __builtin_amdgcn_global_load_lds((const unsigned*)((const char*)(gbase) + (voff)[_i]), (PG8_LAS unsigned*)(lds + (bufoff) + ldsw + _i * 8192), 16, 0, 0); } while (0)
; #define PG8_LDA(dst, b, h) do { _Pragma("unroll") for (int m = 0; m < 4; ++m) _Pragma("unroll") for (int k = 0; k < 2; ++k) dst[m][k] = *(const PG8_LAS bf16x8*)(lds + PG8_SA(b, h) + aoff + m * 2048 + k * 1024); } while (0)
; #define PG8_LDB(dst, b, h) do { _Pragma("unroll") for (int n = 0; n < 2; ++n) _Pragma("unroll") for (int k = 0; k < 2; ++k) dst[n][k] = *(const PG8_LAS bf16x8*)(lds + PG8_SB(b, h) + boff + n * 2048 + k * 1024); } while (0)
; #define PG8_MMA(ai, bj, At, Bt) do { __builtin_amdgcn_s_setprio(1); _Pragma("unroll") for (int m = 0; m < 4; ++m) _Pragma("unroll") for (int n = 0; n < 2; ++n) _Pragma("unroll") for (int k = 0; k < 2; ++k) \
;         acc[ai][bj][m][n] = __builtin_amdgcn_mfma_f32_16x16x32_bf16(Bt[n][k], At[m][k], acc[ai][bj][m][n], 0, 0, 0); __builtin_amdgcn_s_setprio(0); } while (0)
; #define PG8_WAIT_V(n) asm volatile("s_waitcnt vmcnt(" #n ")" ::: "memory")
; #define PG8_WAIT_L(n) asm volatile("s_waitcnt lgkmcnt(" #n ")" ::: "memory")
; #define PG8_BAR __builtin_amdgcn_s_barrier()
; #define PG8_SCHED __builtin_amdgcn_sched_barrier(0)
; template <class Epi, class Sched, bool ALIGN_EPI = false, bool SP2 = false>
; __device__ __forceinline__ void gemm_phase(PG8_LAS unsigned char* lds, const Gemm g, const Sched& S, const Epi& E) {
;     ...
;             PG8_WAIT_V(8); PG8_WAIT_L(0); PG8_BAR; PG8_MMA(1, 0, At, B0); PG8_MMA(1, 1, At, B1); PG8_BAR; PG8_SCHED;
;             PG8_LDB(B0, 1, 0); PG8_LDB(B1, 1, 1); PG8_SCHED; PG8_LDA(At, 1, 0); PG8_STAGE(PG8_SA(0, 1), a2 + hstep, voffA);
;             PG8_WAIT_V(8); PG8_WAIT_L(0); PG8_BAR; PG8_MMA(0, 0, At, B0); PG8_MMA(0, 1, At, B1); PG8_BAR; PG8_SCHED;
	s_setprio 1
	s_waitcnt lgkmcnt(0)
	v_mfma_f32_16x16x32_bf16 v[60:63], v[130:133], v[186:189], 0
	v_mfma_f32_16x16x32_bf16 v[56:59], v[138:141], v[186:189], 0
	v_mfma_f32_16x16x32_bf16 v[40:43], v[138:141], v[216:219], 0
	v_mfma_f32_16x16x32_bf16 v[44:47], v[130:133], v[216:219], 0
	v_mfma_f32_16x16x32_bf16 v[28:31], v[130:133], v[224:227], 0
	v_mfma_f32_16x16x32_bf16 v[24:27], v[138:141], v[224:227], 0
	v_mfma_f32_16x16x32_bf16 v[8:11], v[138:141], v[232:235], 0
	v_mfma_f32_16x16x32_bf16 v[12:15], v[130:133], v[232:235], 0
	v_mfma_f32_16x16x32_bf16 v[60:63], v[134:137], v[190:193], v[60:63]
	v_mfma_f32_16x16x32_bf16 v[56:59], v[142:145], v[190:193], v[56:59]
	v_mfma_f32_16x16x32_bf16 v[40:43], v[142:145], v[220:223], v[40:43]
	v_mfma_f32_16x16x32_bf16 v[44:47], v[134:137], v[220:223], v[44:47]
	v_mfma_f32_16x16x32_bf16 v[28:31], v[134:137], v[228:231], v[28:31]
	v_mfma_f32_16x16x32_bf16 v[24:27], v[142:145], v[228:231], v[24:27]
	v_mfma_f32_16x16x32_bf16 v[8:11], v[142:145], v[236:239], v[8:11]
	v_mfma_f32_16x16x32_bf16 v[12:15], v[134:137], v[236:239], v[12:15]
	v_mfma_f32_16x16x32_bf16 v[52:55], v[158:161], v[186:189], 0
	v_mfma_f32_16x16x32_bf16 v[48:51], v[178:181], v[186:189], 0
	v_mfma_f32_16x16x32_bf16 v[32:35], v[178:181], v[216:219], 0
	v_mfma_f32_16x16x32_bf16 v[36:39], v[158:161], v[216:219], 0
	v_mfma_f32_16x16x32_bf16 v[20:23], v[158:161], v[224:227], 0
	v_mfma_f32_16x16x32_bf16 v[16:19], v[178:181], v[224:227], 0
	v_mfma_f32_16x16x32_bf16 v[0:3], v[178:181], v[232:235], 0
	v_mfma_f32_16x16x32_bf16 v[4:7], v[158:161], v[232:235], 0
	v_mfma_f32_16x16x32_bf16 v[52:55], v[174:177], v[190:193], v[52:55]
	v_mfma_f32_16x16x32_bf16 v[48:51], v[182:185], v[190:193], v[48:51]
	v_mfma_f32_16x16x32_bf16 v[32:35], v[182:185], v[220:223], v[32:35]
	v_mfma_f32_16x16x32_bf16 v[36:39], v[174:177], v[220:223], v[36:39]
	v_mfma_f32_16x16x32_bf16 v[20:23], v[174:177], v[228:231], v[20:23]
	v_mfma_f32_16x16x32_bf16 v[16:19], v[182:185], v[228:231], v[16:19]
	v_mfma_f32_16x16x32_bf16 v[0:3], v[182:185], v[236:239], v[0:3]
	v_mfma_f32_16x16x32_bf16 v[4:7], v[174:177], v[236:239], v[4:7]
	s_setprio 0
	s_barrier
	s_add_i32 s81, 0, 0x18000
	s_add_i32 s92, 0, 0x1c000
	v_add_u32_e32 v142, s81, v213
	v_add_u32_e32 v151, s92, v213
	ds_read_b128 v[130:133], v142
	ds_read_b128 v[134:137], v142 offset:1024
	ds_read_b128 v[138:141], v142 offset:2048
	ds_read_b128 v[142:145], v142 offset:3072
	ds_read_b128 v[158:161], v151
	ds_read_b128 v[174:177], v151 offset:1024
	ds_read_b128 v[178:181], v151 offset:2048
	ds_read_b128 v[182:185], v151 offset:3072
	s_add_u32 s42, s42, s30
	s_addc_u32 s43, s43, 0
	s_mov_b32 m0, s19
	v_lshl_add_u64 v[250:251], s[42:43], 0, v[146:147]
	ds_read_b128 v[186:189], v214 offset:32768
	ds_read_b128 v[190:193], v214 offset:33792
	ds_read_b128 v[216:219], v214 offset:34816
	ds_read_b128 v[220:223], v214 offset:35840
	ds_read_b128 v[224:227], v214 offset:36864
	ds_read_b128 v[228:231], v214 offset:37888
	ds_read_b128 v[232:235], v214 offset:38912
	ds_read_b128 v[236:239], v214 offset:39936
	global_load_lds_dwordx4 v[250:251], off
	s_mov_b32 m0, s20
	v_lshl_add_u64 v[250:251], s[42:43], 0, v[148:149]
	global_load_lds_dwordx4 v[250:251], off
	s_waitcnt vmcnt(8)
	s_waitcnt lgkmcnt(0)
	s_barrier
	s_setprio 1
	s_waitcnt lgkmcnt(0)
	v_mfma_f32_16x16x32_bf16 v[126:129], v[130:133], v[186:189], v[126:129]
	v_mfma_f32_16x16x32_bf16 v[122:125], v[138:141], v[186:189], v[122:125]
	v_mfma_f32_16x16x32_bf16 v[106:109], v[138:141], v[216:219], v[106:109]
	v_mfma_f32_16x16x32_bf16 v[110:113], v[130:133], v[216:219], v[110:113]
	v_mfma_f32_16x16x32_bf16 v[94:97], v[130:133], v[224:227], v[94:97]
	v_mfma_f32_16x16x32_bf16 v[90:93], v[138:141], v[224:227], v[90:93]
	v_mfma_f32_16x16x32_bf16 v[72:75], v[138:141], v[232:235], v[72:75]
	v_mfma_f32_16x16x32_bf16 v[76:79], v[130:133], v[232:235], v[76:79]
	v_mfma_f32_16x16x32_bf16 v[126:129], v[134:137], v[190:193], v[126:129]
	v_mfma_f32_16x16x32_bf16 v[122:125], v[142:145], v[190:193], v[122:125]
	v_mfma_f32_16x16x32_bf16 v[106:109], v[142:145], v[220:223], v[106:109]
	v_mfma_f32_16x16x32_bf16 v[110:113], v[134:137], v[220:223], v[110:113]
	v_mfma_f32_16x16x32_bf16 v[94:97], v[134:137], v[228:231], v[94:97]
	v_mfma_f32_16x16x32_bf16 v[90:93], v[142:145], v[228:231], v[90:93]
	v_mfma_f32_16x16x32_bf16 v[72:75], v[142:145], v[236:239], v[72:75]
	v_mfma_f32_16x16x32_bf16 v[76:79], v[134:137], v[236:239], v[76:79]
	v_mfma_f32_16x16x32_bf16 v[118:121], v[158:161], v[186:189], v[118:121]
	v_mfma_f32_16x16x32_bf16 v[114:117], v[178:181], v[186:189], v[114:117]
	v_mfma_f32_16x16x32_bf16 v[98:101], v[178:181], v[216:219], v[98:101]
	v_mfma_f32_16x16x32_bf16 v[102:105], v[158:161], v[216:219], v[102:105]
	v_mfma_f32_16x16x32_bf16 v[86:89], v[158:161], v[224:227], v[86:89]
	v_mfma_f32_16x16x32_bf16 v[82:85], v[178:181], v[224:227], v[82:85]
	v_mfma_f32_16x16x32_bf16 v[64:67], v[178:181], v[232:235], v[64:67]
	v_mfma_f32_16x16x32_bf16 v[68:71], v[158:161], v[232:235], v[68:71]
	v_mfma_f32_16x16x32_bf16 v[118:121], v[174:177], v[190:193], v[118:121]
	v_mfma_f32_16x16x32_bf16 v[114:117], v[182:185], v[190:193], v[114:117]
	v_mfma_f32_16x16x32_bf16 v[98:101], v[182:185], v[220:223], v[98:101]
	v_mfma_f32_16x16x32_bf16 v[102:105], v[174:177], v[220:223], v[102:105]
	v_mfma_f32_16x16x32_bf16 v[86:89], v[174:177], v[228:231], v[86:89]
	v_mfma_f32_16x16x32_bf16 v[82:85], v[182:185], v[228:231], v[82:85]
	v_mfma_f32_16x16x32_bf16 v[64:67], v[182:185], v[236:239], v[64:67]
	v_mfma_f32_16x16x32_bf16 v[68:71], v[174:177], v[236:239], v[68:71]
	s_setprio 0
	s_barrier
; #define PG8_STAGE(bufoff, gbase, voff) do { _Pragma("unroll") for (int _i = 0; _i < 2; ++_i) \
;         __builtin_amdgcn_global_load_lds((const unsigned*)((const char*)(gbase) + (voff)[_i]), (PG8_LAS unsigned*)(lds + (bufoff) + ldsw + _i * 8192), 16, 0, 0); } while (0)
; #define PG8_LDA(dst, b, h) do { _Pragma("unroll") for (int m = 0; m < 4; ++m) _Pragma("unroll") for (int k = 0; k < 2; ++k) dst[m][k] = *(const PG8_LAS bf16x8*)(lds + PG8_SA(b, h) + aoff + m * 2048 + k * 1024); } while (0)
; #define PG8_LDB(dst, b, h) do { _Pragma("unroll") for (int n = 0; n < 2; ++n) _Pragma("unroll") for (int k = 0; k < 2; ++k) dst[n][k] = *(const PG8_LAS bf16x8*)(lds + PG8_SB(b, h) + boff + n * 2048 + k * 1024); } while (0)
; #define PG8_BAR __builtin_amdgcn_s_barrier()
; template <class Epi, class Sched, bool ALIGN_EPI = false, bool SP2 = false>
; __device__ __forceinline__ void gemm_phase(PG8_LAS unsigned char* lds, const Gemm g, const Sched& S, const Epi& E) {
;     ...
;             const bool last = (t == nt - 2);
;             const char* a1 = cA + (size_t)(t + 1) * kstep;
;             const char* a2 = last ? nA : cA + (size_t)(t + 2) * kstep; const char* b2 = last ? nB : cB + (size_t)(t + 2) * kstep;
;             const char* a3 = a2 + kstep; const char* b3 = b2 + kstep;
;             if (last && has_next) S.a_ready(nxt);
;             if constexpr (SP2) {
;             PG8_LDB(B0, 0, 0); PG8_LDB(B1, 0, 1); PG8_SCHED; PG8_LDA(At, 0, 0); PG8_STAGE(PG8_SA(1, 1), a1 + hstep, voffA);
;             PG8_WAIT_V(8); PG8_WAIT_L(0); PG8_BAR; PG8_MMA(0, 0, At, B0); PG8_MMA(0, 1, At, B1); PG8_BAR; PG8_SCHED;
;             PG8_LDA(At, 0, 1); PG8_STAGE(PG8_SB(0, 0), b2, voffB); PG8_STAGE(PG8_SB(0, 1), b2 + hstep, voffB); PG8_STAGE(PG8_SA(0, 0), a2, voffA);
;             PG8_WAIT_V(8); PG8_WAIT_L(0); PG8_BAR; PG8_MMA(1, 0, At, B0); PG8_MMA(1, 1, At, B1); PG8_BAR; PG8_SCHED;
;             PG8_LDB(B0, 1, 0); PG8_LDB(B1, 1, 1); PG8_SCHED; PG8_LDA(At, 1, 0); PG8_STAGE(PG8_SA(0, 1), a2 + hstep, voffA);
;             PG8_WAIT_V(8); PG8_WAIT_L(0); PG8_BAR; PG8_MMA(0, 0, At, B0); PG8_MMA(0, 1, At, B1); PG8_BAR; PG8_SCHED;
;             PG8_LDA(At, 1, 1); PG8_STAGE(PG8_SB(1, 0), b3, voffB); PG8_STAGE(PG8_SB(1, 1), b3 + hstep, voffB); PG8_STAGE(PG8_SA(1, 0), a3, voffA);
;             PG8_WAIT_V(8); PG8_WAIT_L(0); PG8_BAR; PG8_MMA(1, 0, At, B0); PG8_MMA(1, 1, At, B1); PG8_BAR; PG8_SCHED;
	s_add_i32 s42, s81, s16
	v_lshl_add_u64 v[194:195], v[194:195], 0, s[0:1]
	s_mov_b32 m0, s42
	ds_read_b128 v[186:189], v214 offset:49152
	ds_read_b128 v[190:193], v214 offset:50176
	ds_read_b128 v[216:219], v214 offset:51200
	ds_read_b128 v[220:223], v214 offset:52224
	ds_read_b128 v[224:227], v214 offset:53248
	ds_read_b128 v[228:231], v214 offset:54272
	ds_read_b128 v[232:235], v214 offset:55296
	ds_read_b128 v[236:239], v214 offset:56320
	global_load_lds_dwordx4 v[194:195], off
	v_lshl_add_u64 v[194:195], v[240:241], 0, s[0:1]
	s_add_i32 m0, s42, 0x2000
	s_add_i32 s42, s92, s16
	global_load_lds_dwordx4 v[194:195], off
	s_mov_b32 m0, s42
	v_lshl_add_u64 v[194:195], v[242:243], 0, s[0:1]
	global_load_lds_dwordx4 v[194:195], off
	s_add_i32 m0, s42, 0x2000
	v_lshl_add_u64 v[194:195], v[244:245], 0, s[0:1]
	global_load_lds_dwordx4 v[194:195], off
	s_mov_b32 m0, s8
	v_lshl_add_u64 v[194:195], v[246:247], 0, s[0:1]
	global_load_lds_dwordx4 v[194:195], off
	s_mov_b32 m0, s9
	v_lshl_add_u64 v[194:195], v[248:249], 0, s[0:1]
	global_load_lds_dwordx4 v[194:195], off
	s_waitcnt vmcnt(8)
	s_waitcnt lgkmcnt(0)
	s_barrier
	s_setprio 1
	s_waitcnt lgkmcnt(0)
	v_mfma_f32_16x16x32_bf16 v[60:63], v[130:133], v[186:189], v[60:63]
	v_mfma_f32_16x16x32_bf16 v[56:59], v[138:141], v[186:189], v[56:59]
	v_mfma_f32_16x16x32_bf16 v[40:43], v[138:141], v[216:219], v[40:43]
	v_mfma_f32_16x16x32_bf16 v[44:47], v[130:133], v[216:219], v[44:47]
	v_mfma_f32_16x16x32_bf16 v[28:31], v[130:133], v[224:227], v[28:31]
	v_mfma_f32_16x16x32_bf16 v[24:27], v[138:141], v[224:227], v[24:27]
	v_mfma_f32_16x16x32_bf16 v[8:11], v[138:141], v[232:235], v[8:11]
	v_mfma_f32_16x16x32_bf16 v[12:15], v[130:133], v[232:235], v[12:15]
	v_mfma_f32_16x16x32_bf16 v[60:63], v[134:137], v[190:193], v[60:63]
	v_mfma_f32_16x16x32_bf16 v[56:59], v[142:145], v[190:193], v[56:59]
	v_mfma_f32_16x16x32_bf16 v[40:43], v[142:145], v[220:223], v[40:43]
	v_mfma_f32_16x16x32_bf16 v[44:47], v[134:137], v[220:223], v[44:47]
	v_mfma_f32_16x16x32_bf16 v[28:31], v[134:137], v[228:231], v[28:31]
	v_mfma_f32_16x16x32_bf16 v[24:27], v[142:145], v[228:231], v[24:27]
	v_mfma_f32_16x16x32_bf16 v[8:11], v[142:145], v[236:239], v[8:11]
	v_mfma_f32_16x16x32_bf16 v[12:15], v[134:137], v[236:239], v[12:15]
	v_mfma_f32_16x16x32_bf16 v[52:55], v[158:161], v[186:189], v[52:55]
	v_mfma_f32_16x16x32_bf16 v[48:51], v[178:181], v[186:189], v[48:51]
	v_mfma_f32_16x16x32_bf16 v[32:35], v[178:181], v[216:219], v[32:35]
	v_mfma_f32_16x16x32_bf16 v[36:39], v[158:161], v[216:219], v[36:39]
	v_mfma_f32_16x16x32_bf16 v[20:23], v[158:161], v[224:227], v[20:23]
	v_mfma_f32_16x16x32_bf16 v[16:19], v[178:181], v[224:227], v[16:19]
	v_mfma_f32_16x16x32_bf16 v[0:3], v[178:181], v[232:235], v[0:3]
	v_mfma_f32_16x16x32_bf16 v[4:7], v[158:161], v[232:235], v[4:7]
	v_mfma_f32_16x16x32_bf16 v[52:55], v[174:177], v[190:193], v[52:55]
	v_mfma_f32_16x16x32_bf16 v[48:51], v[182:185], v[190:193], v[48:51]
	v_mfma_f32_16x16x32_bf16 v[32:35], v[182:185], v[220:223], v[32:35]
	v_mfma_f32_16x16x32_bf16 v[36:39], v[174:177], v[220:223], v[36:39]
	v_mfma_f32_16x16x32_bf16 v[20:23], v[174:177], v[228:231], v[20:23]
	v_mfma_f32_16x16x32_bf16 v[16:19], v[182:185], v[228:231], v[16:19]
	v_mfma_f32_16x16x32_bf16 v[0:3], v[182:185], v[236:239], v[0:3]
	v_mfma_f32_16x16x32_bf16 v[4:7], v[174:177], v[236:239], v[4:7]
	s_setprio 0
	s_barrier
	s_add_u32 s38, s38, 0x100
	s_addc_u32 s39, s39, 0
	s_add_u32 s41, s41, 0x100
	s_addc_u32 s45, s45, 0
	s_cmp_ge_u32 s71, s44
	s_mov_b32 s42, s71
	s_cbranch_scc1 .Lpeel_done_0
.LBB0_647:
	s_add_i32 s71, s42, 2
	s_add_u32 s81, s38, 0x80
	s_addc_u32 s43, s39, 0
	s_add_i32 s94, 0, 0x10000
	s_cmp_eq_u32 s24, s42
	s_cselect_b32 s43, s27, s43
	s_cselect_b32 s42, s26, s81
	s_cselect_b32 s93, s91, s45
	s_cselect_b32 s92, s90, s41
	s_add_i32 s81, 0, 0x14000
	v_add_u32_e32 v142, s94, v213
	v_add_u32_e32 v151, s81, v213
	ds_read_b128 v[130:133], v142
	ds_read_b128 v[134:137], v142 offset:1024
	ds_read_b128 v[138:141], v142 offset:2048
	ds_read_b128 v[142:145], v142 offset:3072
	ds_read_b128 v[158:161], v151
	ds_read_b128 v[174:177], v151 offset:1024
	ds_read_b128 v[178:181], v151 offset:2048
	ds_read_b128 v[182:185], v151 offset:3072
	v_lshl_add_u64 v[194:195], s[38:39], 0, v[154:155]
	s_add_i32 m0, s17, 0xc000
	ds_read_b128 v[186:189], v214
	ds_read_b128 v[190:193], v214 offset:1024
	ds_read_b128 v[216:219], v214 offset:2048
	ds_read_b128 v[220:223], v214 offset:3072
	ds_read_b128 v[224:227], v214 offset:4096
	ds_read_b128 v[228:231], v214 offset:5120
	ds_read_b128 v[232:235], v214 offset:6144
	ds_read_b128 v[236:239], v214 offset:7168
	global_load_lds_dwordx4 v[194:195], off
	s_add_i32 m0, s17, 0xe000
	v_lshl_add_u64 v[194:195], s[38:39], 0, v[156:157]
	global_load_lds_dwordx4 v[194:195], off
	s_waitcnt vmcnt(8)
	s_waitcnt lgkmcnt(0)
	s_barrier
; #define PG8_STAGE(bufoff, gbase, voff) do { _Pragma("unroll") for (int _i = 0; _i < 2; ++_i) \
;         __builtin_amdgcn_global_load_lds((const unsigned*)((const char*)(gbase) + (voff)[_i]), (PG8_LAS unsigned*)(lds + (bufoff) + ldsw + _i * 8192), 16, 0, 0); } while (0)
; #define PG8_LDA(dst, b, h) do { _Pragma("unroll") for (int m = 0; m < 4; ++m) _Pragma("unroll") for (int k = 0; k < 2; ++k) dst[m][k] = *(const PG8_LAS bf16x8*)(lds + PG8_SA(b, h) + aoff + m * 2048 + k * 1024); } while (0)
; #define PG8_MMA(ai, bj, At, Bt) do { __builtin_amdgcn_s_setprio(1); _Pragma("unroll") for (int m = 0; m < 4; ++m) _Pragma("unroll") for (int n = 0; n < 2; ++n) _Pragma("unroll") for (int k = 0; k < 2; ++k) \
;         acc[ai][bj][m][n] = __builtin_amdgcn_mfma_f32_16x16x32_bf16(Bt[n][k], At[m][k], acc[ai][bj][m][n], 0, 0, 0); __builtin_amdgcn_s_setprio(0); } while (0)
; #define PG8_WAIT_V(n) asm volatile("s_waitcnt vmcnt(" #n ")" ::: "memory")
; #define PG8_WAIT_L(n) asm volatile("s_waitcnt lgkmcnt(" #n ")" ::: "memory")
; #define PG8_BAR __builtin_amdgcn_s_barrier()
; #define PG8_SCHED __builtin_amdgcn_sched_barrier(0)
; template <class Epi, class Sched, bool ALIGN_EPI = false, bool SP2 = false>
; __device__ __forceinline__ void gemm_phase(PG8_LAS unsigned char* lds, const Gemm g, const Sched& S, const Epi& E) {
;     ...
;             PG8_WAIT_V(8); PG8_WAIT_L(0); PG8_BAR; PG8_MMA(0, 0, At, B0); PG8_MMA(0, 1, At, B1); PG8_BAR; PG8_SCHED;
;             PG8_LDA(At, 0, 1); PG8_STAGE(PG8_SB(0, 0), b2, voffB); PG8_STAGE(PG8_SB(0, 1), b2 + hstep, voffB); PG8_STAGE(PG8_SA(0, 0), a2, voffA);
;             PG8_WAIT_V(8); PG8_WAIT_L(0); PG8_BAR; PG8_MMA(1, 0, At, B0); PG8_MMA(1, 1, At, B1); PG8_BAR; PG8_SCHED;
	s_setprio 1
	s_waitcnt lgkmcnt(0)
	v_mfma_f32_16x16x32_bf16 v[126:129], v[130:133], v[186:189], v[126:129]
	v_mfma_f32_16x16x32_bf16 v[122:125], v[138:141], v[186:189], v[122:125]
	v_mfma_f32_16x16x32_bf16 v[106:109], v[138:141], v[216:219], v[106:109]
	v_mfma_f32_16x16x32_bf16 v[110:113], v[130:133], v[216:219], v[110:113]
	v_mfma_f32_16x16x32_bf16 v[94:97], v[130:133], v[224:227], v[94:97]
	v_mfma_f32_16x16x32_bf16 v[90:93], v[138:141], v[224:227], v[90:93]
	v_mfma_f32_16x16x32_bf16 v[72:75], v[138:141], v[232:235], v[72:75]
	v_mfma_f32_16x16x32_bf16 v[76:79], v[130:133], v[232:235], v[76:79]
	v_mfma_f32_16x16x32_bf16 v[126:129], v[134:137], v[190:193], v[126:129]
	v_mfma_f32_16x16x32_bf16 v[122:125], v[142:145], v[190:193], v[122:125]
	v_mfma_f32_16x16x32_bf16 v[106:109], v[142:145], v[220:223], v[106:109]
	v_mfma_f32_16x16x32_bf16 v[110:113], v[134:137], v[220:223], v[110:113]
	v_mfma_f32_16x16x32_bf16 v[94:97], v[134:137], v[228:231], v[94:97]
	v_mfma_f32_16x16x32_bf16 v[90:93], v[142:145], v[228:231], v[90:93]
	v_mfma_f32_16x16x32_bf16 v[72:75], v[142:145], v[236:239], v[72:75]
	v_mfma_f32_16x16x32_bf16 v[76:79], v[134:137], v[236:239], v[76:79]
	v_mfma_f32_16x16x32_bf16 v[118:121], v[158:161], v[186:189], v[118:121]
	v_mfma_f32_16x16x32_bf16 v[114:117], v[178:181], v[186:189], v[114:117]
	v_mfma_f32_16x16x32_bf16 v[98:101], v[178:181], v[216:219], v[98:101]
	v_mfma_f32_16x16x32_bf16 v[102:105], v[158:161], v[216:219], v[102:105]
	v_mfma_f32_16x16x32_bf16 v[86:89], v[158:161], v[224:227], v[86:89]
	v_mfma_f32_16x16x32_bf16 v[82:85], v[178:181], v[224:227], v[82:85]
	v_mfma_f32_16x16x32_bf16 v[64:67], v[178:181], v[232:235], v[64:67]
	v_mfma_f32_16x16x32_bf16 v[68:71], v[158:161], v[232:235], v[68:71]
	v_mfma_f32_16x16x32_bf16 v[118:121], v[174:177], v[190:193], v[118:121]
	v_mfma_f32_16x16x32_bf16 v[114:117], v[182:185], v[190:193], v[114:117]
	v_mfma_f32_16x16x32_bf16 v[98:101], v[182:185], v[220:223], v[98:101]
	v_mfma_f32_16x16x32_bf16 v[102:105], v[174:177], v[220:223], v[102:105]
	v_mfma_f32_16x16x32_bf16 v[86:89], v[174:177], v[228:231], v[86:89]
	v_mfma_f32_16x16x32_bf16 v[82:85], v[182:185], v[228:231], v[82:85]
	v_mfma_f32_16x16x32_bf16 v[64:67], v[182:185], v[236:239], v[64:67]
	v_mfma_f32_16x16x32_bf16 v[68:71], v[174:177], v[236:239], v[68:71]
	s_setprio 0
	s_barrier
	s_add_i32 s94, s94, s16
	v_lshl_add_u64 v[194:195], s[92:93], 0, v[146:147]
	s_mov_b32 m0, s94
	ds_read_b128 v[186:189], v214 offset:16384
	ds_read_b128 v[190:193], v214 offset:17408
	ds_read_b128 v[216:219], v214 offset:18432
	ds_read_b128 v[220:223], v214 offset:19456
	ds_read_b128 v[224:227], v214 offset:20480
	ds_read_b128 v[228:231], v214 offset:21504
	ds_read_b128 v[232:235], v214 offset:22528
	ds_read_b128 v[236:239], v214 offset:23552
	global_load_lds_dwordx4 v[194:195], off
	s_add_i32 m0, s94, 0x2000
	v_lshl_add_u64 v[240:241], s[92:93], 0, v[148:149]
	s_add_u32 s92, s92, s30
	s_addc_u32 s93, s93, 0
	s_add_i32 s81, s81, s16
	global_load_lds_dwordx4 v[240:241], off
	v_lshl_add_u64 v[242:243], s[92:93], 0, v[146:147]
	s_mov_b32 m0, s81
	v_lshl_add_u64 v[244:245], s[92:93], 0, v[148:149]
	global_load_lds_dwordx4 v[242:243], off
	s_add_i32 m0, s81, 0x2000
	v_lshl_add_u64 v[246:247], s[42:43], 0, v[146:147]
	global_load_lds_dwordx4 v[244:245], off
	s_mov_b32 m0, s17
	v_lshl_add_u64 v[248:249], s[42:43], 0, v[148:149]
	global_load_lds_dwordx4 v[246:247], off
	s_mov_b32 m0, s18
	s_nop 0
	global_load_lds_dwordx4 v[248:249], off
	s_waitcnt vmcnt(8)
	s_waitcnt lgkmcnt(0)
	s_barrier
	s_setprio 1
	s_waitcnt lgkmcnt(0)
	v_mfma_f32_16x16x32_bf16 v[60:63], v[130:133], v[186:189], v[60:63]
	v_mfma_f32_16x16x32_bf16 v[56:59], v[138:141], v[186:189], v[56:59]
	v_mfma_f32_16x16x32_bf16 v[40:43], v[138:141], v[216:219], v[40:43]
	v_mfma_f32_16x16x32_bf16 v[44:47], v[130:133], v[216:219], v[44:47]
	v_mfma_f32_16x16x32_bf16 v[28:31], v[130:133], v[224:227], v[28:31]
	v_mfma_f32_16x16x32_bf16 v[24:27], v[138:141], v[224:227], v[24:27]
	v_mfma_f32_16x16x32_bf16 v[8:11], v[138:141], v[232:235], v[8:11]
	v_mfma_f32_16x16x32_bf16 v[12:15], v[130:133], v[232:235], v[12:15]
	v_mfma_f32_16x16x32_bf16 v[60:63], v[134:137], v[190:193], v[60:63]
	v_mfma_f32_16x16x32_bf16 v[56:59], v[142:145], v[190:193], v[56:59]
	v_mfma_f32_16x16x32_bf16 v[40:43], v[142:145], v[220:223], v[40:43]
	v_mfma_f32_16x16x32_bf16 v[44:47], v[134:137], v[220:223], v[44:47]
	v_mfma_f32_16x16x32_bf16 v[28:31], v[134:137], v[228:231], v[28:31]
	v_mfma_f32_16x16x32_bf16 v[24:27], v[142:145], v[228:231], v[24:27]
	v_mfma_f32_16x16x32_bf16 v[8:11], v[142:145], v[236:239], v[8:11]
	v_mfma_f32_16x16x32_bf16 v[12:15], v[134:137], v[236:239], v[12:15]
	v_mfma_f32_16x16x32_bf16 v[52:55], v[158:161], v[186:189], v[52:55]
	v_mfma_f32_16x16x32_bf16 v[48:51], v[178:181], v[186:189], v[48:51]
	v_mfma_f32_16x16x32_bf16 v[32:35], v[178:181], v[216:219], v[32:35]
	v_mfma_f32_16x16x32_bf16 v[36:39], v[158:161], v[216:219], v[36:39]
	v_mfma_f32_16x16x32_bf16 v[20:23], v[158:161], v[224:227], v[20:23]
	v_mfma_f32_16x16x32_bf16 v[16:19], v[178:181], v[224:227], v[16:19]
	v_mfma_f32_16x16x32_bf16 v[0:3], v[178:181], v[232:235], v[0:3]
	v_mfma_f32_16x16x32_bf16 v[4:7], v[158:161], v[232:235], v[4:7]
	v_mfma_f32_16x16x32_bf16 v[52:55], v[174:177], v[190:193], v[52:55]
	v_mfma_f32_16x16x32_bf16 v[48:51], v[182:185], v[190:193], v[48:51]
	v_mfma_f32_16x16x32_bf16 v[32:35], v[182:185], v[220:223], v[32:35]
	v_mfma_f32_16x16x32_bf16 v[36:39], v[174:177], v[220:223], v[36:39]
	v_mfma_f32_16x16x32_bf16 v[20:23], v[174:177], v[228:231], v[20:23]
	v_mfma_f32_16x16x32_bf16 v[16:19], v[182:185], v[228:231], v[16:19]
	v_mfma_f32_16x16x32_bf16 v[0:3], v[182:185], v[236:239], v[0:3]
	v_mfma_f32_16x16x32_bf16 v[4:7], v[174:177], v[236:239], v[4:7]
	s_setprio 0
	s_barrier
; #define PG8_STAGE(bufoff, gbase, voff) do { _Pragma("unroll") for (int _i = 0; _i < 2; ++_i) \
;         __builtin_amdgcn_global_load_lds((const unsigned*)((const char*)(gbase) + (voff)[_i]), (PG8_LAS unsigned*)(lds + (bufoff) + ldsw + _i * 8192), 16, 0, 0); } while (0)
; #define PG8_LDA(dst, b, h) do { _Pragma("unroll") for (int m = 0; m < 4; ++m) _Pragma("unroll") for (int k = 0; k < 2; ++k) dst[m][k] = *(const PG8_LAS bf16x8*)(lds + PG8_SA(b, h) + aoff + m * 2048 + k * 1024); } while (0)
; #define PG8_LDB(dst, b, h) do { _Pragma("unroll") for (int n = 0; n < 2; ++n) _Pragma("unroll") for (int k = 0; k < 2; ++k) dst[n][k] = *(const PG8_LAS bf16x8*)(lds + PG8_SB(b, h) + boff + n * 2048 + k * 1024); } while (0)
; #define PG8_MMA(ai, bj, At, Bt) do { __builtin_amdgcn_s_setprio(1); _Pragma("unroll") for (int m = 0; m < 4; ++m) _Pragma("unroll") for (int n = 0; n < 2; ++n) _Pragma("unroll") for (int k = 0; k < 2; ++k) \
;         acc[ai][bj][m][n] = __builtin_amdgcn_mfma_f32_16x16x32_bf16(Bt[n][k], At[m][k], acc[ai][bj][m][n], 0, 0, 0); __builtin_amdgcn_s_setprio(0); } while (0)
; #define PG8_WAIT_V(n) asm volatile("s_waitcnt vmcnt(" #n ")" ::: "memory")
; #define PG8_WAIT_L(n) asm volatile("s_waitcnt lgkmcnt(" #n ")" ::: "memory")
; #define PG8_BAR __builtin_amdgcn_s_barrier()
; #define PG8_SCHED __builtin_amdgcn_sched_barrier(0)
; template <class Epi, class Sched, bool ALIGN_EPI = false, bool SP2 = false>
; __device__ __forceinline__ void gemm_phase(PG8_LAS unsigned char* lds, const Gemm g, const Sched& S, const Epi& E) {
;     ...
;             PG8_LDB(B0, 1, 0); PG8_LDB(B1, 1, 1); PG8_SCHED; PG8_LDA(At, 1, 0); PG8_STAGE(PG8_SA(0, 1), a2 + hstep, voffA);
;             PG8_WAIT_V(8); PG8_WAIT_L(0); PG8_BAR; PG8_MMA(0, 0, At, B0); PG8_MMA(0, 1, At, B1); PG8_BAR; PG8_SCHED;
;             PG8_LDA(At, 1, 1); PG8_STAGE(PG8_SB(1, 0), b3, voffB); PG8_STAGE(PG8_SB(1, 1), b3 + hstep, voffB); PG8_STAGE(PG8_SA(1, 0), a3, voffA);
;             PG8_WAIT_V(8); PG8_WAIT_L(0); PG8_BAR; PG8_MMA(1, 0, At, B0); PG8_MMA(1, 1, At, B1); PG8_BAR; PG8_SCHED;
	s_add_i32 s81, 0, 0x18000
	s_add_i32 s92, 0, 0x1c000
	v_add_u32_e32 v142, s81, v213
	v_add_u32_e32 v151, s92, v213
	ds_read_b128 v[130:133], v142
	ds_read_b128 v[134:137], v142 offset:1024
	ds_read_b128 v[138:141], v142 offset:2048
	ds_read_b128 v[142:145], v142 offset:3072
	ds_read_b128 v[158:161], v151
	ds_read_b128 v[174:177], v151 offset:1024
	ds_read_b128 v[178:181], v151 offset:2048
	ds_read_b128 v[182:185], v151 offset:3072
	s_add_u32 s42, s42, s30
	s_addc_u32 s43, s43, 0
	s_mov_b32 m0, s19
	v_lshl_add_u64 v[250:251], s[42:43], 0, v[146:147]
	ds_read_b128 v[186:189], v214 offset:32768
	ds_read_b128 v[190:193], v214 offset:33792
	ds_read_b128 v[216:219], v214 offset:34816
	ds_read_b128 v[220:223], v214 offset:35840
	ds_read_b128 v[224:227], v214 offset:36864
	ds_read_b128 v[228:231], v214 offset:37888
	ds_read_b128 v[232:235], v214 offset:38912
	ds_read_b128 v[236:239], v214 offset:39936
	global_load_lds_dwordx4 v[250:251], off
	s_mov_b32 m0, s20
	v_lshl_add_u64 v[250:251], s[42:43], 0, v[148:149]
	global_load_lds_dwordx4 v[250:251], off
	s_waitcnt vmcnt(8)
	s_waitcnt lgkmcnt(0)
	s_barrier
	s_setprio 1
	s_waitcnt lgkmcnt(0)
	v_mfma_f32_16x16x32_bf16 v[126:129], v[130:133], v[186:189], v[126:129]
	v_mfma_f32_16x16x32_bf16 v[122:125], v[138:141], v[186:189], v[122:125]
	v_mfma_f32_16x16x32_bf16 v[106:109], v[138:141], v[216:219], v[106:109]
	v_mfma_f32_16x16x32_bf16 v[110:113], v[130:133], v[216:219], v[110:113]
	v_mfma_f32_16x16x32_bf16 v[94:97], v[130:133], v[224:227], v[94:97]
	v_mfma_f32_16x16x32_bf16 v[90:93], v[138:141], v[224:227], v[90:93]
	v_mfma_f32_16x16x32_bf16 v[72:75], v[138:141], v[232:235], v[72:75]
	v_mfma_f32_16x16x32_bf16 v[76:79], v[130:133], v[232:235], v[76:79]
	v_mfma_f32_16x16x32_bf16 v[126:129], v[134:137], v[190:193], v[126:129]
	v_mfma_f32_16x16x32_bf16 v[122:125], v[142:145], v[190:193], v[122:125]
	v_mfma_f32_16x16x32_bf16 v[106:109], v[142:145], v[220:223], v[106:109]
	v_mfma_f32_16x16x32_bf16 v[110:113], v[134:137], v[220:223], v[110:113]
	v_mfma_f32_16x16x32_bf16 v[94:97], v[134:137], v[228:231], v[94:97]
	v_mfma_f32_16x16x32_bf16 v[90:93], v[142:145], v[228:231], v[90:93]
	v_mfma_f32_16x16x32_bf16 v[72:75], v[142:145], v[236:239], v[72:75]
	v_mfma_f32_16x16x32_bf16 v[76:79], v[134:137], v[236:239], v[76:79]
	v_mfma_f32_16x16x32_bf16 v[118:121], v[158:161], v[186:189], v[118:121]
	v_mfma_f32_16x16x32_bf16 v[114:117], v[178:181], v[186:189], v[114:117]
	v_mfma_f32_16x16x32_bf16 v[98:101], v[178:181], v[216:219], v[98:101]
	v_mfma_f32_16x16x32_bf16 v[102:105], v[158:161], v[216:219], v[102:105]
	v_mfma_f32_16x16x32_bf16 v[86:89], v[158:161], v[224:227], v[86:89]
	v_mfma_f32_16x16x32_bf16 v[82:85], v[178:181], v[224:227], v[82:85]
	v_mfma_f32_16x16x32_bf16 v[64:67], v[178:181], v[232:235], v[64:67]
	v_mfma_f32_16x16x32_bf16 v[68:71], v[158:161], v[232:235], v[68:71]
	v_mfma_f32_16x16x32_bf16 v[118:121], v[174:177], v[190:193], v[118:121]
	v_mfma_f32_16x16x32_bf16 v[114:117], v[182:185], v[190:193], v[114:117]
	v_mfma_f32_16x16x32_bf16 v[98:101], v[182:185], v[220:223], v[98:101]
	v_mfma_f32_16x16x32_bf16 v[102:105], v[174:177], v[220:223], v[102:105]
	v_mfma_f32_16x16x32_bf16 v[86:89], v[174:177], v[228:231], v[86:89]
	v_mfma_f32_16x16x32_bf16 v[82:85], v[182:185], v[228:231], v[82:85]
	v_mfma_f32_16x16x32_bf16 v[64:67], v[182:185], v[236:239], v[64:67]
	v_mfma_f32_16x16x32_bf16 v[68:71], v[174:177], v[236:239], v[68:71]
	s_setprio 0
	s_barrier
	s_add_i32 s42, s81, s16
	v_lshl_add_u64 v[194:195], v[194:195], 0, s[0:1]
	s_mov_b32 m0, s42
	ds_read_b128 v[186:189], v214 offset:49152
	ds_read_b128 v[190:193], v214 offset:50176
	ds_read_b128 v[216:219], v214 offset:51200
	ds_read_b128 v[220:223], v214 offset:52224
	ds_read_b128 v[224:227], v214 offset:53248
	ds_read_b128 v[228:231], v214 offset:54272
	ds_read_b128 v[232:235], v214 offset:55296
	ds_read_b128 v[236:239], v214 offset:56320
	global_load_lds_dwordx4 v[194:195], off
	v_lshl_add_u64 v[194:195], v[240:241], 0, s[0:1]
	s_add_i32 m0, s42, 0x2000
	s_add_i32 s42, s92, s16
	global_load_lds_dwordx4 v[194:195], off
	s_mov_b32 m0, s42
	v_lshl_add_u64 v[194:195], v[242:243], 0, s[0:1]
	global_load_lds_dwordx4 v[194:195], off
	s_add_i32 m0, s42, 0x2000
	v_lshl_add_u64 v[194:195], v[244:245], 0, s[0:1]
	global_load_lds_dwordx4 v[194:195], off
	s_mov_b32 m0, s8
	v_lshl_add_u64 v[194:195], v[246:247], 0, s[0:1]
	global_load_lds_dwordx4 v[194:195], off
	s_mov_b32 m0, s9
	v_lshl_add_u64 v[194:195], v[248:249], 0, s[0:1]
	global_load_lds_dwordx4 v[194:195], off
	s_waitcnt vmcnt(8)
	s_waitcnt lgkmcnt(0)
	s_barrier
	s_setprio 1
	s_waitcnt lgkmcnt(0)
	v_mfma_f32_16x16x32_bf16 v[60:63], v[130:133], v[186:189], v[60:63]
	v_mfma_f32_16x16x32_bf16 v[56:59], v[138:141], v[186:189], v[56:59]
	v_mfma_f32_16x16x32_bf16 v[40:43], v[138:141], v[216:219], v[40:43]
	v_mfma_f32_16x16x32_bf16 v[44:47], v[130:133], v[216:219], v[44:47]
	v_mfma_f32_16x16x32_bf16 v[28:31], v[130:133], v[224:227], v[28:31]
	v_mfma_f32_16x16x32_bf16 v[24:27], v[138:141], v[224:227], v[24:27]
	v_mfma_f32_16x16x32_bf16 v[8:11], v[138:141], v[232:235], v[8:11]
	v_mfma_f32_16x16x32_bf16 v[12:15], v[130:133], v[232:235], v[12:15]
	v_mfma_f32_16x16x32_bf16 v[60:63], v[134:137], v[190:193], v[60:63]
	v_mfma_f32_16x16x32_bf16 v[56:59], v[142:145], v[190:193], v[56:59]
	v_mfma_f32_16x16x32_bf16 v[40:43], v[142:145], v[220:223], v[40:43]
	v_mfma_f32_16x16x32_bf16 v[44:47], v[134:137], v[220:223], v[44:47]
	v_mfma_f32_16x16x32_bf16 v[28:31], v[134:137], v[228:231], v[28:31]
	v_mfma_f32_16x16x32_bf16 v[24:27], v[142:145], v[228:231], v[24:27]
	v_mfma_f32_16x16x32_bf16 v[8:11], v[142:145], v[236:239], v[8:11]
	v_mfma_f32_16x16x32_bf16 v[12:15], v[134:137], v[236:239], v[12:15]
	v_mfma_f32_16x16x32_bf16 v[52:55], v[158:161], v[186:189], v[52:55]
	v_mfma_f32_16x16x32_bf16 v[48:51], v[178:181], v[186:189], v[48:51]
	v_mfma_f32_16x16x32_bf16 v[32:35], v[178:181], v[216:219], v[32:35]
	v_mfma_f32_16x16x32_bf16 v[36:39], v[158:161], v[216:219], v[36:39]
	v_mfma_f32_16x16x32_bf16 v[20:23], v[158:161], v[224:227], v[20:23]
	v_mfma_f32_16x16x32_bf16 v[16:19], v[178:181], v[224:227], v[16:19]
	v_mfma_f32_16x16x32_bf16 v[0:3], v[178:181], v[232:235], v[0:3]
	v_mfma_f32_16x16x32_bf16 v[4:7], v[158:161], v[232:235], v[4:7]
	v_mfma_f32_16x16x32_bf16 v[52:55], v[174:177], v[190:193], v[52:55]
	v_mfma_f32_16x16x32_bf16 v[48:51], v[182:185], v[190:193], v[48:51]
	v_mfma_f32_16x16x32_bf16 v[32:35], v[182:185], v[220:223], v[32:35]
	v_mfma_f32_16x16x32_bf16 v[36:39], v[174:177], v[220:223], v[36:39]
	v_mfma_f32_16x16x32_bf16 v[20:23], v[174:177], v[228:231], v[20:23]
	v_mfma_f32_16x16x32_bf16 v[16:19], v[182:185], v[228:231], v[16:19]
	v_mfma_f32_16x16x32_bf16 v[0:3], v[182:185], v[236:239], v[0:3]
	v_mfma_f32_16x16x32_bf16 v[4:7], v[174:177], v[236:239], v[4:7]
	s_setprio 0
	s_barrier
	s_add_u32 s38, s38, 0x100
	s_addc_u32 s39, s39, 0
	s_add_u32 s41, s41, 0x100
	s_addc_u32 s45, s45, 0
	s_cmp_ge_u32 s71, s44
	s_mov_b32 s42, s71
	s_cbranch_scc0 .LBB0_647
